# ladder fix extended to the last row group of the rstd-scaled GEMM epilogue: its row statistics are prefetched into the quads freed by group 1 and awaited with a counted vmcnt(8)
# speedup vs baseline: 1.0143x; 1.0066x over previous
.LBB0_83:
	s_add_u32 s4, s0, 0xfff80080
	s_addc_u32 s5, s1, -1
	s_add_i32 s26, 16, 0x10000
	v_add_u32_e32 v151, s26, v148
	ds_read_b128 v[134:137], v151
	ds_read_b128 v[162:165], v151 offset:1024
	ds_read_b128 v[166:169], v151 offset:2048
	ds_read_b128 v[170:173], v151 offset:3072
	s_cmp_eq_u32 s45, 28
	s_cselect_b32 s13, s3, s5
	s_cselect_b32 s12, s15, s4
	s_cselect_b32 s5, s11, s43
	s_cselect_b32 s4, s16, s30
	v_lshl_add_u64 v[152:153], s[0:1], 0, v[130:131]
	s_add_i32 m0, s89, 0xc000
	ds_read_b128 v[174:177], v150
	ds_read_b128 v[186:189], v150 offset:1024
	ds_read_b128 v[190:193], v150 offset:2048
	ds_read_b128 v[194:197], v150 offset:3072
	ds_read_b128 v[198:201], v150 offset:4096
	ds_read_b128 v[202:205], v150 offset:5120
	ds_read_b128 v[206:209], v150 offset:6144
	ds_read_b128 v[210:213], v150 offset:7168
	global_load_lds_dwordx4 v[152:153], off
	v_lshl_add_u64 v[152:153], s[0:1], 0, v[132:133]
	s_add_i32 m0, s89, 0xe000
	s_nop 0
	global_load_lds_dwordx4 v[152:153], off
	s_waitcnt lgkmcnt(8)
	s_barrier
	s_waitcnt lgkmcnt(0)
	s_setprio 1
	s_waitcnt lgkmcnt(0)
	v_mfma_f32_16x16x32_bf16 v[126:129], v[134:137], v[174:177], v[126:129]
	v_mfma_f32_16x16x32_bf16 v[122:125], v[166:169], v[174:177], v[122:125]
	v_mfma_f32_16x16x32_bf16 v[110:113], v[134:137], v[190:193], v[110:113]
	v_mfma_f32_16x16x32_bf16 v[106:109], v[166:169], v[190:193], v[106:109]
	v_mfma_f32_16x16x32_bf16 v[94:97], v[134:137], v[198:201], v[94:97]
	v_mfma_f32_16x16x32_bf16 v[90:93], v[166:169], v[198:201], v[90:93]
	v_mfma_f32_16x16x32_bf16 v[78:81], v[134:137], v[206:209], v[78:81]
	v_mfma_f32_16x16x32_bf16 v[74:77], v[166:169], v[206:209], v[74:77]
	v_mfma_f32_16x16x32_bf16 v[126:129], v[162:165], v[186:189], v[126:129]
	v_mfma_f32_16x16x32_bf16 v[122:125], v[170:173], v[186:189], v[122:125]
	v_mfma_f32_16x16x32_bf16 v[110:113], v[162:165], v[194:197], v[110:113]
	v_mfma_f32_16x16x32_bf16 v[106:109], v[170:173], v[194:197], v[106:109]
	v_mfma_f32_16x16x32_bf16 v[94:97], v[162:165], v[202:205], v[94:97]
	v_mfma_f32_16x16x32_bf16 v[90:93], v[170:173], v[202:205], v[90:93]
	v_mfma_f32_16x16x32_bf16 v[78:81], v[162:165], v[210:213], v[78:81]
	v_mfma_f32_16x16x32_bf16 v[74:77], v[170:173], v[210:213], v[74:77]
	s_setprio 0
	s_barrier
	s_add_i32 s27, 16, 0x14000
	s_add_i32 s26, s26, s18
	v_add_u32_e32 v151, s27, v148
	v_lshl_add_u64 v[152:153], s[4:5], 0, v[156:157]
	s_mov_b32 m0, s26
	ds_read_b128 v[214:217], v151
	ds_read_b128 v[218:221], v151 offset:1024
	ds_read_b128 v[222:225], v151 offset:2048
	ds_read_b128 v[226:229], v151 offset:3072
	global_load_lds_dwordx4 v[152:153], off
	v_lshl_add_u64 v[178:179], s[4:5], 0, v[160:161]
	s_add_i32 m0, s26, 0x2000
	s_nop 0
	global_load_lds_dwordx4 v[178:179], off
	s_barrier
	s_waitcnt lgkmcnt(0)
	s_setprio 1
	s_waitcnt lgkmcnt(0)
	v_mfma_f32_16x16x32_bf16 v[118:121], v[214:217], v[174:177], v[118:121]
	v_mfma_f32_16x16x32_bf16 v[114:117], v[222:225], v[174:177], v[114:117]
	v_mfma_f32_16x16x32_bf16 v[102:105], v[214:217], v[190:193], v[102:105]
	v_mfma_f32_16x16x32_bf16 v[98:101], v[222:225], v[190:193], v[98:101]
	v_mfma_f32_16x16x32_bf16 v[86:89], v[214:217], v[198:201], v[86:89]
	v_mfma_f32_16x16x32_bf16 v[82:85], v[222:225], v[198:201], v[82:85]
	v_mfma_f32_16x16x32_bf16 v[70:73], v[214:217], v[206:209], v[70:73]
	v_mfma_f32_16x16x32_bf16 v[66:69], v[222:225], v[206:209], v[66:69]
	v_mfma_f32_16x16x32_bf16 v[118:121], v[218:221], v[186:189], v[118:121]
	v_mfma_f32_16x16x32_bf16 v[114:117], v[226:229], v[186:189], v[114:117]
	v_mfma_f32_16x16x32_bf16 v[102:105], v[218:221], v[194:197], v[102:105]
	v_mfma_f32_16x16x32_bf16 v[98:101], v[226:229], v[194:197], v[98:101]
	v_mfma_f32_16x16x32_bf16 v[86:89], v[218:221], v[202:205], v[86:89]
	v_mfma_f32_16x16x32_bf16 v[82:85], v[226:229], v[202:205], v[82:85]
	v_mfma_f32_16x16x32_bf16 v[70:73], v[218:221], v[210:213], v[70:73]
	v_mfma_f32_16x16x32_bf16 v[66:69], v[226:229], v[210:213], v[66:69]
	s_setprio 0
	s_mov_b32 m0, s89
	v_lshl_add_u64 v[230:231], s[12:13], 0, v[154:155]
	s_barrier
	ds_read_b128 v[174:177], v150 offset:16384
	ds_read_b128 v[186:189], v150 offset:17408
	ds_read_b128 v[190:193], v150 offset:18432
	ds_read_b128 v[194:197], v150 offset:19456
	ds_read_b128 v[198:201], v150 offset:20480
	ds_read_b128 v[202:205], v150 offset:21504
	ds_read_b128 v[206:209], v150 offset:22528
	ds_read_b128 v[210:213], v150 offset:23552
	global_load_lds_dwordx4 v[230:231], off
	v_lshl_add_u64 v[242:243], s[12:13], 0, v[158:159]
	s_mov_b32 m0, s64
	s_nop 0
	global_load_lds_dwordx4 v[242:243], off
	s_barrier
	s_waitcnt lgkmcnt(0)
	s_setprio 1
	s_waitcnt lgkmcnt(0)
	v_mfma_f32_16x16x32_bf16 v[62:65], v[134:137], v[174:177], v[62:65]
	v_mfma_f32_16x16x32_bf16 v[58:61], v[166:169], v[174:177], v[58:61]
	v_mfma_f32_16x16x32_bf16 v[46:49], v[134:137], v[190:193], v[46:49]
	v_mfma_f32_16x16x32_bf16 v[42:45], v[166:169], v[190:193], v[42:45]
	v_mfma_f32_16x16x32_bf16 v[30:33], v[134:137], v[198:201], v[30:33]
	v_mfma_f32_16x16x32_bf16 v[26:29], v[166:169], v[198:201], v[26:29]
	v_mfma_f32_16x16x32_bf16 v[14:17], v[134:137], v[206:209], v[14:17]
	v_mfma_f32_16x16x32_bf16 v[10:13], v[166:169], v[206:209], v[10:13]
	v_mfma_f32_16x16x32_bf16 v[62:65], v[162:165], v[186:189], v[62:65]
	v_mfma_f32_16x16x32_bf16 v[58:61], v[170:173], v[186:189], v[58:61]
	v_mfma_f32_16x16x32_bf16 v[46:49], v[162:165], v[194:197], v[46:49]
	v_mfma_f32_16x16x32_bf16 v[42:45], v[170:173], v[194:197], v[42:45]
	v_mfma_f32_16x16x32_bf16 v[30:33], v[162:165], v[202:205], v[30:33]
	v_mfma_f32_16x16x32_bf16 v[26:29], v[170:173], v[202:205], v[26:29]
	v_mfma_f32_16x16x32_bf16 v[14:17], v[162:165], v[210:213], v[14:17]
	v_mfma_f32_16x16x32_bf16 v[10:13], v[170:173], v[210:213], v[10:13]
	s_setprio 0
	s_barrier
	s_add_u32 vcc_lo, s4, 0x80000
	s_addc_u32 vcc_hi, s5, 0
	s_add_i32 s26, s27, s18
	v_lshl_add_u64 v[134:135], vcc, 0, v[156:157]
	s_mov_b32 m0, s26
	s_nop 0
	global_load_lds_dwordx4 v[134:135], off
	v_lshl_add_u64 v[134:135], vcc, 0, v[160:161]
	s_add_i32 m0, s26, 0x2000
	s_nop 0
	global_load_lds_dwordx4 v[134:135], off
	s_waitcnt vmcnt(6)
	s_barrier
	s_setprio 1
	v_mfma_f32_16x16x32_bf16 v[54:57], v[214:217], v[174:177], v[54:57]
	v_mfma_f32_16x16x32_bf16 v[50:53], v[222:225], v[174:177], v[50:53]
	v_mfma_f32_16x16x32_bf16 v[38:41], v[214:217], v[190:193], v[38:41]
	v_mfma_f32_16x16x32_bf16 v[34:37], v[222:225], v[190:193], v[34:37]
	v_mfma_f32_16x16x32_bf16 v[22:25], v[214:217], v[198:201], v[22:25]
	v_mfma_f32_16x16x32_bf16 v[18:21], v[222:225], v[198:201], v[18:21]
	v_mfma_f32_16x16x32_bf16 v[6:9], v[214:217], v[206:209], v[6:9]
	v_mfma_f32_16x16x32_bf16 v[2:5], v[222:225], v[206:209], v[2:5]
	v_mfma_f32_16x16x32_bf16 v[54:57], v[218:221], v[186:189], v[54:57]
	v_mfma_f32_16x16x32_bf16 v[50:53], v[226:229], v[186:189], v[50:53]
	v_mfma_f32_16x16x32_bf16 v[38:41], v[218:221], v[194:197], v[38:41]
	v_mfma_f32_16x16x32_bf16 v[34:37], v[226:229], v[194:197], v[34:37]
	v_mfma_f32_16x16x32_bf16 v[22:25], v[218:221], v[202:205], v[22:25]
	v_mfma_f32_16x16x32_bf16 v[18:21], v[226:229], v[202:205], v[18:21]
	v_mfma_f32_16x16x32_bf16 v[6:9], v[218:221], v[210:213], v[6:9]
	v_mfma_f32_16x16x32_bf16 v[2:5], v[226:229], v[210:213], v[2:5]
	s_setprio 0
	s_add_i32 s26, 16, 0x18000
	v_add_u32_e32 v151, s26, v148
	s_barrier
	ds_read_b128 v[134:137], v151
	ds_read_b128 v[162:165], v151 offset:1024
	ds_read_b128 v[166:169], v151 offset:2048
	ds_read_b128 v[170:173], v151 offset:3072
	s_add_u32 s12, s12, 0x80000
	s_addc_u32 s13, s13, 0
	s_mov_b32 m0, s19
	v_lshl_add_u64 v[214:215], s[12:13], 0, v[154:155]
	ds_read_b128 v[174:177], v150 offset:32768
	ds_read_b128 v[186:189], v150 offset:33792
	ds_read_b128 v[190:193], v150 offset:34816
	ds_read_b128 v[194:197], v150 offset:35840
	ds_read_b128 v[198:201], v150 offset:36864
	ds_read_b128 v[202:205], v150 offset:37888
	ds_read_b128 v[206:209], v150 offset:38912
	ds_read_b128 v[210:213], v150 offset:39936
	global_load_lds_dwordx4 v[214:215], off
	v_lshl_add_u64 v[214:215], s[12:13], 0, v[158:159]
	s_mov_b32 m0, s29
	s_nop 0
	global_load_lds_dwordx4 v[214:215], off
	s_waitcnt lgkmcnt(8)
	s_barrier
	s_waitcnt lgkmcnt(0)
	s_setprio 1
	s_waitcnt lgkmcnt(0)
	v_mfma_f32_16x16x32_bf16 v[126:129], v[134:137], v[174:177], v[126:129]
	v_mfma_f32_16x16x32_bf16 v[122:125], v[166:169], v[174:177], v[122:125]
	v_mfma_f32_16x16x32_bf16 v[110:113], v[134:137], v[190:193], v[110:113]
	v_mfma_f32_16x16x32_bf16 v[106:109], v[166:169], v[190:193], v[106:109]
	v_mfma_f32_16x16x32_bf16 v[94:97], v[134:137], v[198:201], v[94:97]
	v_mfma_f32_16x16x32_bf16 v[90:93], v[166:169], v[198:201], v[90:93]
	v_mfma_f32_16x16x32_bf16 v[78:81], v[134:137], v[206:209], v[78:81]
	v_mfma_f32_16x16x32_bf16 v[74:77], v[166:169], v[206:209], v[74:77]
	v_mfma_f32_16x16x32_bf16 v[126:129], v[162:165], v[186:189], v[126:129]
	v_mfma_f32_16x16x32_bf16 v[122:125], v[170:173], v[186:189], v[122:125]
	v_mfma_f32_16x16x32_bf16 v[110:113], v[162:165], v[194:197], v[110:113]
	v_mfma_f32_16x16x32_bf16 v[106:109], v[170:173], v[194:197], v[106:109]
	v_mfma_f32_16x16x32_bf16 v[94:97], v[162:165], v[202:205], v[94:97]
	v_mfma_f32_16x16x32_bf16 v[90:93], v[170:173], v[202:205], v[90:93]
	v_mfma_f32_16x16x32_bf16 v[78:81], v[162:165], v[210:213], v[78:81]
	v_mfma_f32_16x16x32_bf16 v[74:77], v[170:173], v[210:213], v[74:77]
	s_setprio 0
	s_barrier
	s_add_i32 s12, 16, 0x1c000
	s_add_i32 s13, s26, s18
	v_add_u32_e32 v151, s12, v148
	v_lshl_add_u64 v[152:153], v[152:153], 0, s[92:93]
	s_mov_b32 m0, s13
	ds_read_b128 v[214:217], v151
	ds_read_b128 v[218:221], v151 offset:1024
	ds_read_b128 v[222:225], v151 offset:2048
	ds_read_b128 v[226:229], v151 offset:3072
	global_load_lds_dwordx4 v[152:153], off
	v_lshl_add_u64 v[152:153], v[178:179], 0, s[92:93]
	s_add_i32 m0, s13, 0x2000
	s_nop 0
	global_load_lds_dwordx4 v[152:153], off
	s_barrier
	s_waitcnt lgkmcnt(0)
	s_setprio 1
	s_waitcnt lgkmcnt(0)
	v_mfma_f32_16x16x32_bf16 v[118:121], v[214:217], v[174:177], v[118:121]
	v_mfma_f32_16x16x32_bf16 v[114:117], v[222:225], v[174:177], v[114:117]
	v_mfma_f32_16x16x32_bf16 v[102:105], v[214:217], v[190:193], v[102:105]
	v_mfma_f32_16x16x32_bf16 v[98:101], v[222:225], v[190:193], v[98:101]
	v_mfma_f32_16x16x32_bf16 v[86:89], v[214:217], v[198:201], v[86:89]
	v_mfma_f32_16x16x32_bf16 v[82:85], v[222:225], v[198:201], v[82:85]
	v_mfma_f32_16x16x32_bf16 v[70:73], v[214:217], v[206:209], v[70:73]
	v_mfma_f32_16x16x32_bf16 v[66:69], v[222:225], v[206:209], v[66:69]
	v_mfma_f32_16x16x32_bf16 v[118:121], v[218:221], v[186:189], v[118:121]
	v_mfma_f32_16x16x32_bf16 v[114:117], v[226:229], v[186:189], v[114:117]
	v_mfma_f32_16x16x32_bf16 v[102:105], v[218:221], v[194:197], v[102:105]
	v_mfma_f32_16x16x32_bf16 v[98:101], v[226:229], v[194:197], v[98:101]
	v_mfma_f32_16x16x32_bf16 v[86:89], v[218:221], v[202:205], v[86:89]
	v_mfma_f32_16x16x32_bf16 v[82:85], v[226:229], v[202:205], v[82:85]
	v_mfma_f32_16x16x32_bf16 v[70:73], v[218:221], v[210:213], v[70:73]
	v_mfma_f32_16x16x32_bf16 v[66:69], v[226:229], v[210:213], v[66:69]
	s_setprio 0
	s_mov_b32 m0, s28
	v_lshl_add_u64 v[152:153], v[230:231], 0, s[92:93]
	s_barrier
	ds_read_b128 v[174:177], v150 offset:49152
	ds_read_b128 v[186:189], v150 offset:50176
	ds_read_b128 v[190:193], v150 offset:51200
	ds_read_b128 v[194:197], v150 offset:52224
	ds_read_b128 v[198:201], v150 offset:53248
	ds_read_b128 v[202:205], v150 offset:54272
	ds_read_b128 v[206:209], v150 offset:55296
	ds_read_b128 v[210:213], v150 offset:56320
	global_load_lds_dwordx4 v[152:153], off
	v_lshl_add_u64 v[152:153], v[242:243], 0, s[92:93]
	s_mov_b32 m0, s88
	s_nop 0
	global_load_lds_dwordx4 v[152:153], off
	s_barrier
	s_waitcnt lgkmcnt(0)
	s_setprio 1
	s_waitcnt lgkmcnt(0)
	v_mfma_f32_16x16x32_bf16 v[62:65], v[134:137], v[174:177], v[62:65]
	v_mfma_f32_16x16x32_bf16 v[58:61], v[166:169], v[174:177], v[58:61]
	v_mfma_f32_16x16x32_bf16 v[46:49], v[134:137], v[190:193], v[46:49]
	v_mfma_f32_16x16x32_bf16 v[42:45], v[166:169], v[190:193], v[42:45]
	v_mfma_f32_16x16x32_bf16 v[30:33], v[134:137], v[198:201], v[30:33]
	v_mfma_f32_16x16x32_bf16 v[26:29], v[166:169], v[198:201], v[26:29]
	v_mfma_f32_16x16x32_bf16 v[14:17], v[134:137], v[206:209], v[14:17]
	v_mfma_f32_16x16x32_bf16 v[10:13], v[166:169], v[206:209], v[10:13]
	v_mfma_f32_16x16x32_bf16 v[62:65], v[162:165], v[186:189], v[62:65]
	v_mfma_f32_16x16x32_bf16 v[58:61], v[170:173], v[186:189], v[58:61]
	v_mfma_f32_16x16x32_bf16 v[46:49], v[162:165], v[194:197], v[46:49]
	v_mfma_f32_16x16x32_bf16 v[42:45], v[170:173], v[194:197], v[42:45]
	v_mfma_f32_16x16x32_bf16 v[30:33], v[162:165], v[202:205], v[30:33]
	v_mfma_f32_16x16x32_bf16 v[26:29], v[170:173], v[202:205], v[26:29]
	v_mfma_f32_16x16x32_bf16 v[14:17], v[162:165], v[210:213], v[14:17]
	v_mfma_f32_16x16x32_bf16 v[10:13], v[170:173], v[210:213], v[10:13]
	s_setprio 0
	s_barrier
	s_add_u32 s4, s4, 0x80080
	s_addc_u32 s5, s5, 0
	s_add_i32 s12, s12, s18
	v_lshl_add_u64 v[134:135], s[4:5], 0, v[156:157]
	s_mov_b32 m0, s12
	s_nop 0
	global_load_lds_dwordx4 v[134:135], off
	v_lshl_add_u64 v[134:135], s[4:5], 0, v[160:161]
	s_add_i32 m0, s12, 0x2000
	s_nop 0
	global_load_lds_dwordx4 v[134:135], off
	s_waitcnt vmcnt(6)
	s_barrier
	s_setprio 1
	v_mfma_f32_16x16x32_bf16 v[54:57], v[214:217], v[174:177], v[54:57]
	v_mfma_f32_16x16x32_bf16 v[50:53], v[222:225], v[174:177], v[50:53]
	v_mfma_f32_16x16x32_bf16 v[38:41], v[214:217], v[190:193], v[38:41]
	v_mfma_f32_16x16x32_bf16 v[34:37], v[222:225], v[190:193], v[34:37]
	v_mfma_f32_16x16x32_bf16 v[22:25], v[214:217], v[198:201], v[22:25]
	v_mfma_f32_16x16x32_bf16 v[18:21], v[222:225], v[198:201], v[18:21]
	v_mfma_f32_16x16x32_bf16 v[6:9], v[214:217], v[206:209], v[6:9]
	v_mfma_f32_16x16x32_bf16 v[2:5], v[222:225], v[206:209], v[2:5]
	v_mfma_f32_16x16x32_bf16 v[54:57], v[218:221], v[186:189], v[54:57]
	v_mfma_f32_16x16x32_bf16 v[50:53], v[226:229], v[186:189], v[50:53]
	v_mfma_f32_16x16x32_bf16 v[38:41], v[218:221], v[194:197], v[38:41]
	v_mfma_f32_16x16x32_bf16 v[34:37], v[226:229], v[194:197], v[34:37]
	v_mfma_f32_16x16x32_bf16 v[22:25], v[218:221], v[202:205], v[22:25]
	v_mfma_f32_16x16x32_bf16 v[18:21], v[226:229], v[202:205], v[18:21]
	v_mfma_f32_16x16x32_bf16 v[6:9], v[218:221], v[210:213], v[6:9]
	v_mfma_f32_16x16x32_bf16 v[2:5], v[226:229], v[210:213], v[2:5]
	s_setprio 0
	s_add_i32 s45, s45, 2
	s_add_u32 s0, s0, 0x100
	s_addc_u32 s1, s1, 0
	s_add_u32 s30, s30, 0x100
	s_addc_u32 s43, s43, 0
	s_cmp_gt_u32 s45, 29
	s_barrier
	s_cbranch_scc0 .LBB0_83
	v_lshl_add_u32 v134, s42, 8, v147
	v_ashrrev_i32_e32 v135, 31, v134
	v_readlane_b32 s4, v252, 24
	v_lshlrev_b64 v[162:163], 5, v[134:135]
	v_readlane_b32 s5, v252, 25
	v_lshlrev_b64 v[152:153], 12, v[134:135]
	s_mov_b32 s11, 0xf800000
	v_lshl_add_u64 v[166:167], s[4:5], 0, v[162:163]
	global_load_dwordx4 v[162:165], v[166:167], off
	s_nop 0
	global_load_dwordx4 v[166:169], v[166:167], off offset:16
	v_or_b32_e32 v176, 16, v134
	v_ashrrev_i32_e32 v177, 31, v176
	v_lshlrev_b64 v[176:177], 5, v[176:177]
	v_lshl_add_u64 v[176:177], s[4:5], 0, v[176:177]
	global_load_dwordx4 v[186:189], v[176:177], off
	global_load_dwordx4 v[190:193], v[176:177], off offset:16
	v_or_b32_e32 v176, 32, v134
	v_ashrrev_i32_e32 v177, 31, v176
	v_lshlrev_b64 v[176:177], 5, v[176:177]
	v_lshl_add_u64 v[176:177], s[4:5], 0, v[176:177]
	global_load_dwordx4 v[194:197], v[176:177], off
	global_load_dwordx4 v[198:201], v[176:177], off offset:16
	v_or_b32_e32 v176, 48, v134
	v_ashrrev_i32_e32 v177, 31, v176
	v_lshlrev_b64 v[176:177], 5, v[176:177]
	v_lshl_add_u64 v[176:177], s[4:5], 0, v[176:177]
	global_load_dwordx4 v[202:205], v[176:177], off
	global_load_dwordx4 v[206:209], v[176:177], off offset:16
	v_add_u32_e32 v176, 0x80, v134
	v_ashrrev_i32_e32 v177, 31, v176
	v_lshlrev_b64 v[176:177], 5, v[176:177]
	v_lshl_add_u64 v[176:177], s[4:5], 0, v[176:177]
	global_load_dwordx4 v[210:213], v[176:177], off
	global_load_dwordx4 v[214:217], v[176:177], off offset:16
	v_add_u32_e32 v176, 0x90, v134
	v_ashrrev_i32_e32 v177, 31, v176
	v_lshlrev_b64 v[176:177], 5, v[176:177]
	v_lshl_add_u64 v[176:177], s[4:5], 0, v[176:177]
	global_load_dwordx4 v[218:221], v[176:177], off
	global_load_dwordx4 v[222:225], v[176:177], off offset:16
	v_add_u32_e32 v176, 0xa0, v134
	v_ashrrev_i32_e32 v177, 31, v176
	v_lshlrev_b64 v[176:177], 5, v[176:177]
	v_lshl_add_u64 v[176:177], s[4:5], 0, v[176:177]
	global_load_dwordx4 v[226:229], v[176:177], off
	global_load_dwordx4 v[172:175], v[176:177], off offset:16
	v_lshl_or_b32 v136, s2, 8, v149
	v_readlane_b32 s2, v252, 14
	v_ashrrev_i32_e32 v137, 31, v136
	v_readlane_b32 s3, v252, 15
	v_lshlrev_b64 v[136:137], 1, v[136:137]
	s_mov_b64 s[12:13], s[24:25]
	v_lshl_add_u64 v[152:153], s[2:3], 0, v[152:153]
	v_lshl_add_u64 v[152:153], v[152:153], 0, v[136:137]
	s_mov_b32 s16, 0x1a000
	s_waitcnt vmcnt(0)
	v_mov_b32_e32 v170, v162
	v_mov_b32_e32 v171, v166
	v_mov_b32_e32 v166, v163
	v_pk_add_f32 v[162:163], v[170:171], v[166:167]
	v_mov_b32_e32 v166, v164
	v_mov_b32_e32 v167, v168
	v_mov_b32_e32 v168, v165
	v_pk_add_f32 v[164:165], v[166:167], v[168:169]
	s_nop 0
	v_pk_add_f32 v[162:163], v[162:163], v[164:165]
	s_nop 0
	v_add_f32_e32 v135, v162, v163
	v_fmamk_f32 v135, v135, 0x3a000000, v233
	v_cmp_gt_f32_e32 vcc, s11, v135
	v_mul_f32_e32 v151, 0x4f800000, v135
	s_nop 0
	v_cndmask_b32_e32 v135, v135, v151, vcc
	v_sqrt_f32_e32 v151, v135
	s_nop 0
	v_add_u32_e32 v162, -1, v151
	v_fma_f32 v163, -v162, v151, v135
	v_cmp_ge_f32_e64 s[42:43], 0, v163
	v_add_u32_e32 v163, 1, v151
	s_nop 0
	v_cndmask_b32_e64 v162, v151, v162, s[42:43]
	v_fma_f32 v151, -v163, v151, v135
	v_cmp_lt_f32_e64 s[42:43], 0, v151
	s_nop 1
	v_cndmask_b32_e64 v151, v162, v163, s[42:43]
	v_mul_f32_e32 v162, 0x37800000, v151
	v_cndmask_b32_e32 v151, v151, v162, vcc
	v_cmp_class_f32_e32 vcc, v135, v234
	s_nop 1
	v_cndmask_b32_e32 v135, v151, v135, vcc
	v_div_scale_f32 v151, s[0:1], v135, v135, 1.0
	v_rcp_f32_e32 v162, v151
	s_nop 0
	v_fma_f32 v163, -v151, v162, 1.0
	v_fmac_f32_e32 v162, v163, v162
	v_div_scale_f32 v163, vcc, 1.0, v135, 1.0
	v_mul_f32_e32 v164, v163, v162
	v_fma_f32 v165, -v151, v164, v163
	v_fmac_f32_e32 v164, v165, v162
	v_fma_f32 v151, -v151, v164, v163
	v_div_fmas_f32 v151, v151, v162, v164
	v_div_fixup_f32 v162, v151, v135, 1.0
	v_pk_mul_f32 v[128:129], v[128:129], v[162:163] op_sel_hi:[1,0]
	v_pk_mul_f32 v[126:127], v[126:127], v[162:163] op_sel_hi:[1,0]
	v_pk_mul_f32 v[164:165], v[124:125], v[162:163] op_sel_hi:[1,0]
	v_pk_mul_f32 v[124:125], v[122:123], v[162:163] op_sel_hi:[1,0]
	v_cvt_pk_bf16_f32 v122, v126, v127
	v_cvt_pk_bf16_f32 v123, v128, v129
	v_cvt_pk_bf16_f32 v124, v124, v125
	v_cvt_pk_bf16_f32 v125, v164, v165
	global_store_dwordx4 v[152:153], v[122:125], off
	v_pk_mul_f32 v[120:121], v[120:121], v[162:163] op_sel_hi:[1,0]
	v_pk_mul_f32 v[118:119], v[118:119], v[162:163] op_sel_hi:[1,0]
	v_pk_mul_f32 v[122:123], v[116:117], v[162:163] op_sel_hi:[1,0]
	v_pk_mul_f32 v[116:117], v[114:115], v[162:163] op_sel_hi:[1,0]
	v_cvt_pk_bf16_f32 v114, v118, v119
	v_cvt_pk_bf16_f32 v115, v120, v121
	v_cvt_pk_bf16_f32 v116, v116, v117
	v_cvt_pk_bf16_f32 v117, v122, v123
	global_store_dwordx4 v[152:153], v[114:117], off offset:256
	s_nop 1
	v_or_b32_e32 v116, 16, v134
	v_ashrrev_i32_e32 v117, 31, v116
	v_lshlrev_b64 v[114:115], 12, v[116:117]
	v_lshlrev_b64 v[116:117], 5, v[116:117]
	v_lshl_add_u64 v[120:121], s[4:5], 0, v[116:117]
	s_nop 0
	v_lshl_add_u64 v[114:115], s[2:3], 0, v[114:115]
	v_lshl_add_u64 v[114:115], v[114:115], 0, v[136:137]
	v_mov_b32_e32 v116, v186
	v_mov_b32_e32 v117, v187
	v_mov_b32_e32 v118, v188
	v_mov_b32_e32 v119, v189
	v_mov_b32_e32 v120, v190
	v_mov_b32_e32 v121, v191
	v_mov_b32_e32 v122, v192
	v_mov_b32_e32 v123, v193
	v_add_u32_e32 v176, 0xb0, v134
	v_ashrrev_i32_e32 v177, 31, v176
	v_lshlrev_b64 v[176:177], 5, v[176:177]
	v_lshl_add_u64 v[176:177], s[4:5], 0, v[176:177]
	global_load_dwordx4 v[186:189], v[176:177], off
	global_load_dwordx4 v[190:193], v[176:177], off offset:16
	v_mov_b32_e32 v124, v116
	v_mov_b32_e32 v125, v120
	v_mov_b32_e32 v120, v117
	v_pk_add_f32 v[116:117], v[124:125], v[120:121]
	v_mov_b32_e32 v120, v118
	v_mov_b32_e32 v121, v122
	v_mov_b32_e32 v122, v119
	v_pk_add_f32 v[118:119], v[120:121], v[122:123]
	s_nop 0
	v_pk_add_f32 v[116:117], v[116:117], v[118:119]
	s_nop 0
	v_add_f32_e32 v116, v116, v117
	v_fmamk_f32 v116, v116, 0x3a000000, v233
	v_cmp_gt_f32_e32 vcc, s11, v116
	v_mul_f32_e32 v117, 0x4f800000, v116
	s_nop 0
	v_cndmask_b32_e32 v116, v116, v117, vcc
	v_sqrt_f32_e32 v117, v116
	s_nop 0
	v_add_u32_e32 v118, -1, v117
	v_fma_f32 v119, -v118, v117, v116
	v_cmp_ge_f32_e64 s[42:43], 0, v119
	v_add_u32_e32 v119, 1, v117
	s_nop 0
	v_cndmask_b32_e64 v118, v117, v118, s[42:43]
	v_fma_f32 v117, -v119, v117, v116
	v_cmp_lt_f32_e64 s[42:43], 0, v117
	s_nop 1
	v_cndmask_b32_e64 v117, v118, v119, s[42:43]
	v_mul_f32_e32 v118, 0x37800000, v117
	v_cndmask_b32_e32 v117, v117, v118, vcc
	v_cmp_class_f32_e32 vcc, v116, v234
	s_nop 1
	v_cndmask_b32_e32 v116, v117, v116, vcc
	v_div_scale_f32 v117, s[0:1], v116, v116, 1.0
	v_rcp_f32_e32 v118, v117
	s_nop 0
	v_fma_f32 v119, -v117, v118, 1.0
	v_fmac_f32_e32 v118, v119, v118
	v_div_scale_f32 v119, vcc, 1.0, v116, 1.0
	v_mul_f32_e32 v120, v119, v118
	v_fma_f32 v121, -v117, v120, v119
	v_fmac_f32_e32 v120, v121, v118
	v_fma_f32 v117, -v117, v120, v119
	v_div_fmas_f32 v117, v117, v118, v120
	v_div_fixup_f32 v116, v117, v116, 1.0
	v_pk_mul_f32 v[112:113], v[112:113], v[116:117] op_sel_hi:[1,0]
	v_pk_mul_f32 v[110:111], v[110:111], v[116:117] op_sel_hi:[1,0]
	v_pk_mul_f32 v[118:119], v[108:109], v[116:117] op_sel_hi:[1,0]
	v_pk_mul_f32 v[108:109], v[106:107], v[116:117] op_sel_hi:[1,0]
	v_cvt_pk_bf16_f32 v106, v110, v111
	v_cvt_pk_bf16_f32 v107, v112, v113
	v_cvt_pk_bf16_f32 v108, v108, v109
	v_cvt_pk_bf16_f32 v109, v118, v119
	global_store_dwordx4 v[114:115], v[106:109], off
	v_pk_mul_f32 v[104:105], v[104:105], v[116:117] op_sel_hi:[1,0]
	v_pk_mul_f32 v[102:103], v[102:103], v[116:117] op_sel_hi:[1,0]
	v_pk_mul_f32 v[106:107], v[100:101], v[116:117] op_sel_hi:[1,0]
	v_pk_mul_f32 v[100:101], v[98:99], v[116:117] op_sel_hi:[1,0]
	v_cvt_pk_bf16_f32 v98, v102, v103
	v_cvt_pk_bf16_f32 v99, v104, v105
	v_cvt_pk_bf16_f32 v100, v100, v101
	v_cvt_pk_bf16_f32 v101, v106, v107
	global_store_dwordx4 v[114:115], v[98:101], off offset:256
	s_nop 1
	v_or_b32_e32 v100, 32, v134
	v_ashrrev_i32_e32 v101, 31, v100
	v_lshlrev_b64 v[98:99], 12, v[100:101]
	v_lshlrev_b64 v[100:101], 5, v[100:101]
	v_lshl_add_u64 v[104:105], s[4:5], 0, v[100:101]
	s_nop 0
	v_lshl_add_u64 v[98:99], s[2:3], 0, v[98:99]
	v_lshl_add_u64 v[98:99], v[98:99], 0, v[136:137]
	v_mov_b32_e32 v100, v194
	v_mov_b32_e32 v101, v195
	v_mov_b32_e32 v102, v196
	v_mov_b32_e32 v103, v197
	v_mov_b32_e32 v104, v198
	v_mov_b32_e32 v105, v199
	v_mov_b32_e32 v106, v200
	v_mov_b32_e32 v107, v201
	v_mov_b32_e32 v108, v100
	v_mov_b32_e32 v109, v104
	v_mov_b32_e32 v104, v101
	v_pk_add_f32 v[100:101], v[108:109], v[104:105]
	v_mov_b32_e32 v104, v102
	v_mov_b32_e32 v105, v106
	v_mov_b32_e32 v106, v103
	v_pk_add_f32 v[102:103], v[104:105], v[106:107]
	s_nop 0
	v_pk_add_f32 v[100:101], v[100:101], v[102:103]
	s_nop 0
	v_add_f32_e32 v100, v100, v101
	v_fmamk_f32 v100, v100, 0x3a000000, v233
	v_cmp_gt_f32_e32 vcc, s11, v100
	v_mul_f32_e32 v101, 0x4f800000, v100
	s_nop 0
	v_cndmask_b32_e32 v100, v100, v101, vcc
	v_sqrt_f32_e32 v101, v100
	s_nop 0
	v_add_u32_e32 v102, -1, v101
	v_fma_f32 v103, -v102, v101, v100
	v_cmp_ge_f32_e64 s[42:43], 0, v103
	v_add_u32_e32 v103, 1, v101
	s_nop 0
	v_cndmask_b32_e64 v102, v101, v102, s[42:43]
	v_fma_f32 v101, -v103, v101, v100
	v_cmp_lt_f32_e64 s[42:43], 0, v101
	s_nop 1
	v_cndmask_b32_e64 v101, v102, v103, s[42:43]
	v_mul_f32_e32 v102, 0x37800000, v101
	v_cndmask_b32_e32 v101, v101, v102, vcc
	v_cmp_class_f32_e32 vcc, v100, v234
	s_nop 1
	v_cndmask_b32_e32 v100, v101, v100, vcc
	v_div_scale_f32 v101, s[0:1], v100, v100, 1.0
	v_rcp_f32_e32 v102, v101
	s_nop 0
	v_fma_f32 v103, -v101, v102, 1.0
	v_fmac_f32_e32 v102, v103, v102
	v_div_scale_f32 v103, vcc, 1.0, v100, 1.0
	v_mul_f32_e32 v104, v103, v102
	v_fma_f32 v105, -v101, v104, v103
	v_fmac_f32_e32 v104, v105, v102
	v_fma_f32 v101, -v101, v104, v103
	v_div_fmas_f32 v101, v101, v102, v104
	v_div_fixup_f32 v100, v101, v100, 1.0
	v_pk_mul_f32 v[96:97], v[96:97], v[100:101] op_sel_hi:[1,0]
	v_pk_mul_f32 v[94:95], v[94:95], v[100:101] op_sel_hi:[1,0]
	v_pk_mul_f32 v[102:103], v[92:93], v[100:101] op_sel_hi:[1,0]
	v_pk_mul_f32 v[92:93], v[90:91], v[100:101] op_sel_hi:[1,0]
	v_cvt_pk_bf16_f32 v90, v94, v95
	v_cvt_pk_bf16_f32 v91, v96, v97
	v_cvt_pk_bf16_f32 v92, v92, v93
	v_cvt_pk_bf16_f32 v93, v102, v103
	global_store_dwordx4 v[98:99], v[90:93], off
	v_pk_mul_f32 v[88:89], v[88:89], v[100:101] op_sel_hi:[1,0]
	v_pk_mul_f32 v[86:87], v[86:87], v[100:101] op_sel_hi:[1,0]
	v_pk_mul_f32 v[90:91], v[84:85], v[100:101] op_sel_hi:[1,0]
	v_pk_mul_f32 v[84:85], v[82:83], v[100:101] op_sel_hi:[1,0]
	v_cvt_pk_bf16_f32 v82, v86, v87
	v_cvt_pk_bf16_f32 v83, v88, v89
	v_cvt_pk_bf16_f32 v84, v84, v85
	v_cvt_pk_bf16_f32 v85, v90, v91
	global_store_dwordx4 v[98:99], v[82:85], off offset:256
	s_nop 1
	v_or_b32_e32 v84, 48, v134
	v_ashrrev_i32_e32 v85, 31, v84
	v_lshlrev_b64 v[82:83], 12, v[84:85]
	v_lshlrev_b64 v[84:85], 5, v[84:85]
	v_lshl_add_u64 v[88:89], s[4:5], 0, v[84:85]
	s_nop 0
	v_lshl_add_u64 v[82:83], s[2:3], 0, v[82:83]
	v_lshl_add_u64 v[82:83], v[82:83], 0, v[136:137]
	v_mov_b32_e32 v84, v202
	v_mov_b32_e32 v85, v203
	v_mov_b32_e32 v86, v204
	v_mov_b32_e32 v87, v205
	v_mov_b32_e32 v88, v206
	v_mov_b32_e32 v89, v207
	v_mov_b32_e32 v90, v208
	v_mov_b32_e32 v91, v209
	v_mov_b32_e32 v92, v84
	v_mov_b32_e32 v93, v88
	v_mov_b32_e32 v88, v85
	v_pk_add_f32 v[84:85], v[92:93], v[88:89]
	v_mov_b32_e32 v88, v86
	v_mov_b32_e32 v89, v90
	v_mov_b32_e32 v90, v87
	v_pk_add_f32 v[86:87], v[88:89], v[90:91]
	s_nop 0
	v_pk_add_f32 v[84:85], v[84:85], v[86:87]
	s_nop 0
	v_add_f32_e32 v84, v84, v85
	v_fmamk_f32 v84, v84, 0x3a000000, v233
	v_cmp_gt_f32_e32 vcc, s11, v84
	v_mul_f32_e32 v85, 0x4f800000, v84
	s_nop 0
	v_cndmask_b32_e32 v84, v84, v85, vcc
	v_sqrt_f32_e32 v85, v84
	s_nop 0
	v_add_u32_e32 v86, -1, v85
	v_fma_f32 v87, -v86, v85, v84
	v_cmp_ge_f32_e64 s[42:43], 0, v87
	v_add_u32_e32 v87, 1, v85
	s_nop 0
	v_cndmask_b32_e64 v86, v85, v86, s[42:43]
	v_fma_f32 v85, -v87, v85, v84
	v_cmp_lt_f32_e64 s[42:43], 0, v85
	s_nop 1
	v_cndmask_b32_e64 v85, v86, v87, s[42:43]
	v_mul_f32_e32 v86, 0x37800000, v85
	v_cndmask_b32_e32 v85, v85, v86, vcc
	v_cmp_class_f32_e32 vcc, v84, v234
	s_nop 1
	v_cndmask_b32_e32 v84, v85, v84, vcc
	v_div_scale_f32 v85, s[0:1], v84, v84, 1.0
	v_rcp_f32_e32 v86, v85
	s_nop 0
	v_fma_f32 v87, -v85, v86, 1.0
	v_fmac_f32_e32 v86, v87, v86
	v_div_scale_f32 v87, vcc, 1.0, v84, 1.0
	v_mul_f32_e32 v88, v87, v86
	v_fma_f32 v89, -v85, v88, v87
	v_fmac_f32_e32 v88, v89, v86
	v_fma_f32 v85, -v85, v88, v87
	v_div_fmas_f32 v85, v85, v86, v88
	v_div_fixup_f32 v84, v85, v84, 1.0
	v_pk_mul_f32 v[80:81], v[80:81], v[84:85] op_sel_hi:[1,0]
	v_pk_mul_f32 v[78:79], v[78:79], v[84:85] op_sel_hi:[1,0]
	v_pk_mul_f32 v[86:87], v[76:77], v[84:85] op_sel_hi:[1,0]
	v_pk_mul_f32 v[76:77], v[74:75], v[84:85] op_sel_hi:[1,0]
	v_cvt_pk_bf16_f32 v74, v78, v79
	v_cvt_pk_bf16_f32 v75, v80, v81
	v_cvt_pk_bf16_f32 v76, v76, v77
	v_cvt_pk_bf16_f32 v77, v86, v87
	global_store_dwordx4 v[82:83], v[74:77], off
	v_pk_mul_f32 v[72:73], v[72:73], v[84:85] op_sel_hi:[1,0]
	v_pk_mul_f32 v[70:71], v[70:71], v[84:85] op_sel_hi:[1,0]
	v_pk_mul_f32 v[74:75], v[68:69], v[84:85] op_sel_hi:[1,0]
	v_pk_mul_f32 v[68:69], v[66:67], v[84:85] op_sel_hi:[1,0]
	v_cvt_pk_bf16_f32 v66, v70, v71
	v_cvt_pk_bf16_f32 v67, v72, v73
	v_cvt_pk_bf16_f32 v68, v68, v69
	v_cvt_pk_bf16_f32 v69, v74, v75
	global_store_dwordx4 v[82:83], v[66:69], off offset:256
	s_nop 1
	v_add_u32_e32 v68, 0x80, v134
	v_ashrrev_i32_e32 v69, 31, v68
	v_lshlrev_b64 v[66:67], 12, v[68:69]
	v_lshlrev_b64 v[68:69], 5, v[68:69]
	v_lshl_add_u64 v[72:73], s[4:5], 0, v[68:69]
	s_nop 0
	v_lshl_add_u64 v[66:67], s[2:3], 0, v[66:67]
	v_lshl_add_u64 v[66:67], v[66:67], 0, v[136:137]
	v_mov_b32_e32 v68, v210
	v_mov_b32_e32 v69, v211
	v_mov_b32_e32 v70, v212
	v_mov_b32_e32 v71, v213
	v_mov_b32_e32 v72, v214
	v_mov_b32_e32 v73, v215
	v_mov_b32_e32 v74, v216
	v_mov_b32_e32 v75, v217
	v_mov_b32_e32 v76, v68
	v_mov_b32_e32 v77, v72
	v_mov_b32_e32 v72, v69
	v_pk_add_f32 v[68:69], v[76:77], v[72:73]
	v_mov_b32_e32 v72, v70
	v_mov_b32_e32 v73, v74
	v_mov_b32_e32 v74, v71
	v_pk_add_f32 v[70:71], v[72:73], v[74:75]
	s_nop 0
	v_pk_add_f32 v[68:69], v[68:69], v[70:71]
	s_nop 0
	v_add_f32_e32 v68, v68, v69
	v_fmamk_f32 v68, v68, 0x3a000000, v233
	v_cmp_gt_f32_e32 vcc, s11, v68
	v_mul_f32_e32 v69, 0x4f800000, v68
	s_nop 0
	v_cndmask_b32_e32 v68, v68, v69, vcc
	v_sqrt_f32_e32 v69, v68
	s_nop 0
	v_add_u32_e32 v70, -1, v69
	v_fma_f32 v71, -v70, v69, v68
	v_cmp_ge_f32_e64 s[42:43], 0, v71
	v_add_u32_e32 v71, 1, v69
	s_nop 0
	v_cndmask_b32_e64 v70, v69, v70, s[42:43]
	v_fma_f32 v69, -v71, v69, v68
	v_cmp_lt_f32_e64 s[42:43], 0, v69
	s_nop 1
	v_cndmask_b32_e64 v69, v70, v71, s[42:43]
	v_mul_f32_e32 v70, 0x37800000, v69
	v_cndmask_b32_e32 v69, v69, v70, vcc
	v_cmp_class_f32_e32 vcc, v68, v234
	s_nop 1
	v_cndmask_b32_e32 v68, v69, v68, vcc
	v_div_scale_f32 v69, s[0:1], v68, v68, 1.0
	v_rcp_f32_e32 v70, v69
	s_nop 0
	v_fma_f32 v71, -v69, v70, 1.0
	v_fmac_f32_e32 v70, v71, v70
	v_div_scale_f32 v71, vcc, 1.0, v68, 1.0
	v_mul_f32_e32 v72, v71, v70
	v_fma_f32 v73, -v69, v72, v71
	v_fmac_f32_e32 v72, v73, v70
	v_fma_f32 v69, -v69, v72, v71
	v_div_fmas_f32 v69, v69, v70, v72
	v_div_fixup_f32 v68, v69, v68, 1.0
	v_pk_mul_f32 v[64:65], v[64:65], v[68:69] op_sel_hi:[1,0]
	v_pk_mul_f32 v[62:63], v[62:63], v[68:69] op_sel_hi:[1,0]
	v_pk_mul_f32 v[70:71], v[60:61], v[68:69] op_sel_hi:[1,0]
	v_pk_mul_f32 v[60:61], v[58:59], v[68:69] op_sel_hi:[1,0]
	v_cvt_pk_bf16_f32 v58, v62, v63
	v_cvt_pk_bf16_f32 v59, v64, v65
	v_cvt_pk_bf16_f32 v60, v60, v61
	v_cvt_pk_bf16_f32 v61, v70, v71
	global_store_dwordx4 v[66:67], v[58:61], off
	v_pk_mul_f32 v[56:57], v[56:57], v[68:69] op_sel_hi:[1,0]
	v_pk_mul_f32 v[54:55], v[54:55], v[68:69] op_sel_hi:[1,0]
	v_pk_mul_f32 v[58:59], v[52:53], v[68:69] op_sel_hi:[1,0]
	v_pk_mul_f32 v[52:53], v[50:51], v[68:69] op_sel_hi:[1,0]
	v_cvt_pk_bf16_f32 v50, v54, v55
	v_cvt_pk_bf16_f32 v51, v56, v57
	v_cvt_pk_bf16_f32 v52, v52, v53
	v_cvt_pk_bf16_f32 v53, v58, v59
	global_store_dwordx4 v[66:67], v[50:53], off offset:256
	s_nop 1
	v_add_u32_e32 v52, 0x90, v134
	v_ashrrev_i32_e32 v53, 31, v52
	v_lshlrev_b64 v[50:51], 12, v[52:53]
	v_lshlrev_b64 v[52:53], 5, v[52:53]
	v_lshl_add_u64 v[56:57], s[4:5], 0, v[52:53]
	s_nop 0
	v_lshl_add_u64 v[50:51], s[2:3], 0, v[50:51]
	v_lshl_add_u64 v[50:51], v[50:51], 0, v[136:137]
	v_mov_b32_e32 v52, v218
	v_mov_b32_e32 v53, v219
	v_mov_b32_e32 v54, v220
	v_mov_b32_e32 v55, v221
	v_mov_b32_e32 v56, v222
	v_mov_b32_e32 v57, v223
	v_mov_b32_e32 v58, v224
	v_mov_b32_e32 v59, v225
	v_mov_b32_e32 v60, v52
	v_mov_b32_e32 v61, v56
	v_mov_b32_e32 v56, v53
	v_pk_add_f32 v[52:53], v[60:61], v[56:57]
	v_mov_b32_e32 v56, v54
	v_mov_b32_e32 v57, v58
	v_mov_b32_e32 v58, v55
	v_pk_add_f32 v[54:55], v[56:57], v[58:59]
	s_nop 0
	v_pk_add_f32 v[52:53], v[52:53], v[54:55]
	s_nop 0
	v_add_f32_e32 v52, v52, v53
	v_fmamk_f32 v52, v52, 0x3a000000, v233
	v_cmp_gt_f32_e32 vcc, s11, v52
	v_mul_f32_e32 v53, 0x4f800000, v52
	s_nop 0
	v_cndmask_b32_e32 v52, v52, v53, vcc
	v_sqrt_f32_e32 v53, v52
	s_nop 0
	v_add_u32_e32 v54, -1, v53
	v_fma_f32 v55, -v54, v53, v52
	v_cmp_ge_f32_e64 s[42:43], 0, v55
	v_add_u32_e32 v55, 1, v53
	s_nop 0
	v_cndmask_b32_e64 v54, v53, v54, s[42:43]
	v_fma_f32 v53, -v55, v53, v52
	v_cmp_lt_f32_e64 s[42:43], 0, v53
	s_nop 1
	v_cndmask_b32_e64 v53, v54, v55, s[42:43]
	v_mul_f32_e32 v54, 0x37800000, v53
	v_cndmask_b32_e32 v53, v53, v54, vcc
	v_cmp_class_f32_e32 vcc, v52, v234
	s_nop 1
	v_cndmask_b32_e32 v52, v53, v52, vcc
	v_div_scale_f32 v53, s[0:1], v52, v52, 1.0
	v_rcp_f32_e32 v54, v53
	s_nop 0
	v_fma_f32 v55, -v53, v54, 1.0
	v_fmac_f32_e32 v54, v55, v54
	v_div_scale_f32 v55, vcc, 1.0, v52, 1.0
	v_mul_f32_e32 v56, v55, v54
	v_fma_f32 v57, -v53, v56, v55
	v_fmac_f32_e32 v56, v57, v54
	v_fma_f32 v53, -v53, v56, v55
	v_div_fmas_f32 v53, v53, v54, v56
	v_div_fixup_f32 v52, v53, v52, 1.0
	v_pk_mul_f32 v[48:49], v[48:49], v[52:53] op_sel_hi:[1,0]
	v_pk_mul_f32 v[46:47], v[46:47], v[52:53] op_sel_hi:[1,0]
	v_pk_mul_f32 v[54:55], v[44:45], v[52:53] op_sel_hi:[1,0]
	v_pk_mul_f32 v[44:45], v[42:43], v[52:53] op_sel_hi:[1,0]
	v_cvt_pk_bf16_f32 v42, v46, v47
	v_cvt_pk_bf16_f32 v43, v48, v49
	v_cvt_pk_bf16_f32 v44, v44, v45
	v_cvt_pk_bf16_f32 v45, v54, v55
	global_store_dwordx4 v[50:51], v[42:45], off
	v_pk_mul_f32 v[40:41], v[40:41], v[52:53] op_sel_hi:[1,0]
	v_pk_mul_f32 v[38:39], v[38:39], v[52:53] op_sel_hi:[1,0]
	v_pk_mul_f32 v[42:43], v[36:37], v[52:53] op_sel_hi:[1,0]
	v_pk_mul_f32 v[36:37], v[34:35], v[52:53] op_sel_hi:[1,0]
	v_cvt_pk_bf16_f32 v34, v38, v39
	v_cvt_pk_bf16_f32 v35, v40, v41
	v_cvt_pk_bf16_f32 v36, v36, v37
	v_cvt_pk_bf16_f32 v37, v42, v43
	global_store_dwordx4 v[50:51], v[34:37], off offset:256
	s_nop 1
	v_add_u32_e32 v36, 0xa0, v134
	v_ashrrev_i32_e32 v37, 31, v36
	v_lshlrev_b64 v[34:35], 12, v[36:37]
	v_lshlrev_b64 v[36:37], 5, v[36:37]
	v_lshl_add_u64 v[40:41], s[4:5], 0, v[36:37]
	s_nop 0
	v_lshl_add_u64 v[34:35], s[2:3], 0, v[34:35]
	v_lshl_add_u64 v[34:35], v[34:35], 0, v[136:137]
	v_mov_b32_e32 v36, v226
	v_mov_b32_e32 v37, v227
	v_mov_b32_e32 v38, v228
	v_mov_b32_e32 v39, v229
	v_mov_b32_e32 v40, v172
	v_mov_b32_e32 v41, v173
	v_mov_b32_e32 v42, v174
	v_mov_b32_e32 v43, v175
	v_mov_b32_e32 v44, v36
	v_mov_b32_e32 v45, v40
	v_mov_b32_e32 v40, v37
	v_pk_add_f32 v[36:37], v[44:45], v[40:41]
	v_mov_b32_e32 v40, v38
	v_mov_b32_e32 v41, v42
	v_mov_b32_e32 v42, v39
	v_pk_add_f32 v[38:39], v[40:41], v[42:43]
	s_nop 0
	v_pk_add_f32 v[36:37], v[36:37], v[38:39]
	s_nop 0
	v_add_f32_e32 v36, v36, v37
	v_fmamk_f32 v36, v36, 0x3a000000, v233
	v_cmp_gt_f32_e32 vcc, s11, v36
	v_mul_f32_e32 v37, 0x4f800000, v36
	s_nop 0
	v_cndmask_b32_e32 v36, v36, v37, vcc
	v_sqrt_f32_e32 v37, v36
	s_nop 0
	v_add_u32_e32 v38, -1, v37
	v_fma_f32 v39, -v38, v37, v36
	v_cmp_ge_f32_e64 s[42:43], 0, v39
	v_add_u32_e32 v39, 1, v37
	s_nop 0
	v_cndmask_b32_e64 v38, v37, v38, s[42:43]
	v_fma_f32 v37, -v39, v37, v36
	v_cmp_lt_f32_e64 s[42:43], 0, v37
	s_nop 1
	v_cndmask_b32_e64 v37, v38, v39, s[42:43]
	v_mul_f32_e32 v38, 0x37800000, v37
	v_cndmask_b32_e32 v37, v37, v38, vcc
	v_cmp_class_f32_e32 vcc, v36, v234
	s_nop 1
	v_cndmask_b32_e32 v36, v37, v36, vcc
	v_div_scale_f32 v37, s[0:1], v36, v36, 1.0
	v_rcp_f32_e32 v38, v37
	s_nop 0
	v_fma_f32 v39, -v37, v38, 1.0
	v_fmac_f32_e32 v38, v39, v38
	v_div_scale_f32 v39, vcc, 1.0, v36, 1.0
	v_mul_f32_e32 v40, v39, v38
	v_fma_f32 v41, -v37, v40, v39
	v_fmac_f32_e32 v40, v41, v38
	v_fma_f32 v37, -v37, v40, v39
	v_div_fmas_f32 v37, v37, v38, v40
	v_div_fixup_f32 v36, v37, v36, 1.0
	v_pk_mul_f32 v[32:33], v[32:33], v[36:37] op_sel_hi:[1,0]
	v_pk_mul_f32 v[30:31], v[30:31], v[36:37] op_sel_hi:[1,0]
	v_pk_mul_f32 v[38:39], v[28:29], v[36:37] op_sel_hi:[1,0]
	v_pk_mul_f32 v[28:29], v[26:27], v[36:37] op_sel_hi:[1,0]
	v_cvt_pk_bf16_f32 v26, v30, v31
	v_cvt_pk_bf16_f32 v27, v32, v33
	v_cvt_pk_bf16_f32 v28, v28, v29
	v_cvt_pk_bf16_f32 v29, v38, v39
	global_store_dwordx4 v[34:35], v[26:29], off
	v_pk_mul_f32 v[24:25], v[24:25], v[36:37] op_sel_hi:[1,0]
	v_pk_mul_f32 v[22:23], v[22:23], v[36:37] op_sel_hi:[1,0]
	v_pk_mul_f32 v[26:27], v[20:21], v[36:37] op_sel_hi:[1,0]
	v_pk_mul_f32 v[20:21], v[18:19], v[36:37] op_sel_hi:[1,0]
	v_cvt_pk_bf16_f32 v18, v22, v23
	v_cvt_pk_bf16_f32 v19, v24, v25
	v_cvt_pk_bf16_f32 v20, v20, v21
	v_cvt_pk_bf16_f32 v21, v26, v27
	global_store_dwordx4 v[34:35], v[18:21], off offset:256
	s_nop 1
	v_add_u32_e32 v20, 0xb0, v134
	v_ashrrev_i32_e32 v21, 31, v20
	v_lshlrev_b64 v[18:19], 12, v[20:21]
	v_lshlrev_b64 v[20:21], 5, v[20:21]
	v_lshl_add_u64 v[24:25], s[4:5], 0, v[20:21]
	s_nop 0
	v_lshl_add_u64 v[18:19], s[2:3], 0, v[18:19]
	v_lshl_add_u64 v[18:19], v[18:19], 0, v[136:137]
	s_mov_b32 s2, s10
	s_waitcnt vmcnt(8)
	v_mov_b32_e32 v20, v186
	v_mov_b32_e32 v21, v187
	v_mov_b32_e32 v22, v188
	v_mov_b32_e32 v23, v189
	v_mov_b32_e32 v24, v190
	v_mov_b32_e32 v25, v191
	v_mov_b32_e32 v26, v192
	v_mov_b32_e32 v27, v193
	v_mov_b32_e32 v28, v20
	v_mov_b32_e32 v29, v24
	v_mov_b32_e32 v24, v21
	v_pk_add_f32 v[20:21], v[28:29], v[24:25]
	v_mov_b32_e32 v24, v22
	v_mov_b32_e32 v25, v26
	v_mov_b32_e32 v26, v23
	v_pk_add_f32 v[22:23], v[24:25], v[26:27]
	s_nop 0
	v_pk_add_f32 v[20:21], v[20:21], v[22:23]
	s_nop 0
	v_add_f32_e32 v20, v20, v21
	v_fmamk_f32 v20, v20, 0x3a000000, v233
	v_cmp_gt_f32_e32 vcc, s11, v20
	v_mul_f32_e32 v21, 0x4f800000, v20
	s_nop 0
	v_cndmask_b32_e32 v20, v20, v21, vcc
	v_sqrt_f32_e32 v21, v20
	s_nop 0
	v_add_u32_e32 v22, -1, v21
	v_fma_f32 v23, -v22, v21, v20
	v_cmp_ge_f32_e64 s[42:43], 0, v23
	v_add_u32_e32 v23, 1, v21
	s_nop 0
	v_cndmask_b32_e64 v22, v21, v22, s[42:43]
	v_fma_f32 v21, -v23, v21, v20
	v_cmp_lt_f32_e64 s[42:43], 0, v21
	s_nop 1
	v_cndmask_b32_e64 v21, v22, v23, s[42:43]
	v_mul_f32_e32 v22, 0x37800000, v21
	v_cndmask_b32_e32 v21, v21, v22, vcc
	v_cmp_class_f32_e32 vcc, v20, v234
	s_mov_b32 s42, s14
	s_nop 0
	v_cndmask_b32_e32 v20, v21, v20, vcc
	v_div_scale_f32 v21, s[0:1], v20, v20, 1.0
	v_rcp_f32_e32 v22, v21
	s_mov_b64 s[0:1], s[46:47]
	v_readlane_b32 s46, v255, 49
	v_fma_f32 v23, -v21, v22, 1.0
	v_fmac_f32_e32 v22, v23, v22
	v_div_scale_f32 v23, vcc, 1.0, v20, 1.0
	v_mul_f32_e32 v24, v23, v22
	v_fma_f32 v25, -v21, v24, v23
	v_fmac_f32_e32 v24, v25, v22
	v_fma_f32 v21, -v21, v24, v23
	v_div_fmas_f32 v21, v21, v22, v24
	v_div_fixup_f32 v20, v21, v20, 1.0
	v_pk_mul_f32 v[16:17], v[16:17], v[20:21] op_sel_hi:[1,0]
	v_pk_mul_f32 v[14:15], v[14:15], v[20:21] op_sel_hi:[1,0]
	v_pk_mul_f32 v[22:23], v[12:13], v[20:21] op_sel_hi:[1,0]
	v_pk_mul_f32 v[12:13], v[10:11], v[20:21] op_sel_hi:[1,0]
	v_cvt_pk_bf16_f32 v10, v14, v15
	v_cvt_pk_bf16_f32 v11, v16, v17
	v_cvt_pk_bf16_f32 v12, v12, v13
	v_cvt_pk_bf16_f32 v13, v22, v23
	global_store_dwordx4 v[18:19], v[10:13], off
	v_pk_mul_f32 v[8:9], v[8:9], v[20:21] op_sel_hi:[1,0]
	v_pk_mul_f32 v[6:7], v[6:7], v[20:21] op_sel_hi:[1,0]
	v_pk_mul_f32 v[10:11], v[4:5], v[20:21] op_sel_hi:[1,0]
	v_pk_mul_f32 v[4:5], v[2:3], v[20:21] op_sel_hi:[1,0]
	v_cvt_pk_bf16_f32 v2, v6, v7
	v_cvt_pk_bf16_f32 v3, v8, v9
	v_cvt_pk_bf16_f32 v4, v4, v5
	v_cvt_pk_bf16_f32 v5, v10, v11
	s_and_b64 vcc, exec, s[40:41]
	global_store_dwordx4 v[18:19], v[2:5], off offset:256
	s_cbranch_vccz .LBB0_76
	s_waitcnt vmcnt(0)
	s_cmpk_gt_u32 s55, 0xff
	s_cbranch_scc1 .LBB0_87
	s_barrier

.LBB0_104:
	s_add_u32 s4, s0, 0xfff80080
	s_addc_u32 s5, s1, -1
	s_add_i32 s26, 16, 0x10000
	v_add_u32_e32 v151, s26, v148
	ds_read_b128 v[134:137], v151
	ds_read_b128 v[162:165], v151 offset:1024
	ds_read_b128 v[166:169], v151 offset:2048
	ds_read_b128 v[170:173], v151 offset:3072
	s_cmp_eq_u32 s47, 28
	s_cselect_b32 s13, s3, s5
	s_cselect_b32 s12, s15, s4
	s_cselect_b32 s5, s11, s45
	s_cselect_b32 s4, s16, s30
	v_lshl_add_u64 v[152:153], s[0:1], 0, v[130:131]
	s_add_i32 m0, s88, 0xc000
	ds_read_b128 v[174:177], v150
	ds_read_b128 v[186:189], v150 offset:1024
	ds_read_b128 v[190:193], v150 offset:2048
	ds_read_b128 v[194:197], v150 offset:3072
	ds_read_b128 v[198:201], v150 offset:4096
	ds_read_b128 v[202:205], v150 offset:5120
	ds_read_b128 v[206:209], v150 offset:6144
	ds_read_b128 v[210:213], v150 offset:7168
	global_load_lds_dwordx4 v[152:153], off
	v_lshl_add_u64 v[152:153], s[0:1], 0, v[132:133]
	s_add_i32 m0, s88, 0xe000
	s_nop 0
	global_load_lds_dwordx4 v[152:153], off
	s_waitcnt lgkmcnt(8)
	s_barrier
	s_waitcnt lgkmcnt(0)
	s_setprio 1
	s_waitcnt lgkmcnt(0)
	v_mfma_f32_16x16x32_bf16 v[126:129], v[134:137], v[174:177], v[126:129]
	v_mfma_f32_16x16x32_bf16 v[122:125], v[166:169], v[174:177], v[122:125]
	v_mfma_f32_16x16x32_bf16 v[110:113], v[134:137], v[190:193], v[110:113]
	v_mfma_f32_16x16x32_bf16 v[106:109], v[166:169], v[190:193], v[106:109]
	v_mfma_f32_16x16x32_bf16 v[94:97], v[134:137], v[198:201], v[94:97]
	v_mfma_f32_16x16x32_bf16 v[90:93], v[166:169], v[198:201], v[90:93]
	v_mfma_f32_16x16x32_bf16 v[78:81], v[134:137], v[206:209], v[78:81]
	v_mfma_f32_16x16x32_bf16 v[74:77], v[166:169], v[206:209], v[74:77]
	v_mfma_f32_16x16x32_bf16 v[126:129], v[162:165], v[186:189], v[126:129]
	v_mfma_f32_16x16x32_bf16 v[122:125], v[170:173], v[186:189], v[122:125]
	v_mfma_f32_16x16x32_bf16 v[110:113], v[162:165], v[194:197], v[110:113]
	v_mfma_f32_16x16x32_bf16 v[106:109], v[170:173], v[194:197], v[106:109]
	v_mfma_f32_16x16x32_bf16 v[94:97], v[162:165], v[202:205], v[94:97]
	v_mfma_f32_16x16x32_bf16 v[90:93], v[170:173], v[202:205], v[90:93]
	v_mfma_f32_16x16x32_bf16 v[78:81], v[162:165], v[210:213], v[78:81]
	v_mfma_f32_16x16x32_bf16 v[74:77], v[170:173], v[210:213], v[74:77]
	s_setprio 0
	s_barrier
	s_add_i32 s27, 16, 0x14000
	s_add_i32 s26, s26, s18
	v_add_u32_e32 v151, s27, v148
	v_lshl_add_u64 v[152:153], s[4:5], 0, v[156:157]
	s_mov_b32 m0, s26
	ds_read_b128 v[214:217], v151
	ds_read_b128 v[218:221], v151 offset:1024
	ds_read_b128 v[222:225], v151 offset:2048
	ds_read_b128 v[226:229], v151 offset:3072
	global_load_lds_dwordx4 v[152:153], off
	v_lshl_add_u64 v[178:179], s[4:5], 0, v[160:161]
	s_add_i32 m0, s26, 0x2000
	s_nop 0
	global_load_lds_dwordx4 v[178:179], off
	s_barrier
	s_waitcnt lgkmcnt(0)
	s_setprio 1
	s_waitcnt lgkmcnt(0)
	v_mfma_f32_16x16x32_bf16 v[118:121], v[214:217], v[174:177], v[118:121]
	v_mfma_f32_16x16x32_bf16 v[114:117], v[222:225], v[174:177], v[114:117]
	v_mfma_f32_16x16x32_bf16 v[102:105], v[214:217], v[190:193], v[102:105]
	v_mfma_f32_16x16x32_bf16 v[98:101], v[222:225], v[190:193], v[98:101]
	v_mfma_f32_16x16x32_bf16 v[86:89], v[214:217], v[198:201], v[86:89]
	v_mfma_f32_16x16x32_bf16 v[82:85], v[222:225], v[198:201], v[82:85]
	v_mfma_f32_16x16x32_bf16 v[70:73], v[214:217], v[206:209], v[70:73]
	v_mfma_f32_16x16x32_bf16 v[66:69], v[222:225], v[206:209], v[66:69]
	v_mfma_f32_16x16x32_bf16 v[118:121], v[218:221], v[186:189], v[118:121]
	v_mfma_f32_16x16x32_bf16 v[114:117], v[226:229], v[186:189], v[114:117]
	v_mfma_f32_16x16x32_bf16 v[102:105], v[218:221], v[194:197], v[102:105]
	v_mfma_f32_16x16x32_bf16 v[98:101], v[226:229], v[194:197], v[98:101]
	v_mfma_f32_16x16x32_bf16 v[86:89], v[218:221], v[202:205], v[86:89]
	v_mfma_f32_16x16x32_bf16 v[82:85], v[226:229], v[202:205], v[82:85]
	v_mfma_f32_16x16x32_bf16 v[70:73], v[218:221], v[210:213], v[70:73]
	v_mfma_f32_16x16x32_bf16 v[66:69], v[226:229], v[210:213], v[66:69]
	s_setprio 0
	s_mov_b32 m0, s88
	v_lshl_add_u64 v[230:231], s[12:13], 0, v[154:155]
	s_barrier
	ds_read_b128 v[174:177], v150 offset:16384
	ds_read_b128 v[186:189], v150 offset:17408
	ds_read_b128 v[190:193], v150 offset:18432
	ds_read_b128 v[194:197], v150 offset:19456
	ds_read_b128 v[198:201], v150 offset:20480
	ds_read_b128 v[202:205], v150 offset:21504
	ds_read_b128 v[206:209], v150 offset:22528
	ds_read_b128 v[210:213], v150 offset:23552
	global_load_lds_dwordx4 v[230:231], off
	v_lshl_add_u64 v[242:243], s[12:13], 0, v[158:159]
	s_mov_b32 m0, s89
	s_nop 0
	global_load_lds_dwordx4 v[242:243], off
	s_barrier
	s_waitcnt lgkmcnt(0)
	s_setprio 1
	s_waitcnt lgkmcnt(0)
	v_mfma_f32_16x16x32_bf16 v[62:65], v[134:137], v[174:177], v[62:65]
	v_mfma_f32_16x16x32_bf16 v[58:61], v[166:169], v[174:177], v[58:61]
	v_mfma_f32_16x16x32_bf16 v[46:49], v[134:137], v[190:193], v[46:49]
	v_mfma_f32_16x16x32_bf16 v[42:45], v[166:169], v[190:193], v[42:45]
	v_mfma_f32_16x16x32_bf16 v[30:33], v[134:137], v[198:201], v[30:33]
	v_mfma_f32_16x16x32_bf16 v[26:29], v[166:169], v[198:201], v[26:29]
	v_mfma_f32_16x16x32_bf16 v[14:17], v[134:137], v[206:209], v[14:17]
	v_mfma_f32_16x16x32_bf16 v[10:13], v[166:169], v[206:209], v[10:13]
	v_mfma_f32_16x16x32_bf16 v[62:65], v[162:165], v[186:189], v[62:65]
	v_mfma_f32_16x16x32_bf16 v[58:61], v[170:173], v[186:189], v[58:61]
	v_mfma_f32_16x16x32_bf16 v[46:49], v[162:165], v[194:197], v[46:49]
	v_mfma_f32_16x16x32_bf16 v[42:45], v[170:173], v[194:197], v[42:45]
	v_mfma_f32_16x16x32_bf16 v[30:33], v[162:165], v[202:205], v[30:33]
	v_mfma_f32_16x16x32_bf16 v[26:29], v[170:173], v[202:205], v[26:29]
	v_mfma_f32_16x16x32_bf16 v[14:17], v[162:165], v[210:213], v[14:17]
	v_mfma_f32_16x16x32_bf16 v[10:13], v[170:173], v[210:213], v[10:13]
	s_setprio 0
	s_barrier
	s_add_u32 vcc_lo, s4, 0x80000
	s_addc_u32 vcc_hi, s5, 0
	s_add_i32 s26, s27, s18
	v_lshl_add_u64 v[134:135], vcc, 0, v[156:157]
	s_mov_b32 m0, s26
	s_nop 0
	global_load_lds_dwordx4 v[134:135], off
	v_lshl_add_u64 v[134:135], vcc, 0, v[160:161]
	s_add_i32 m0, s26, 0x2000
	s_nop 0
	global_load_lds_dwordx4 v[134:135], off
	s_waitcnt vmcnt(6)
	s_barrier
	s_setprio 1
	v_mfma_f32_16x16x32_bf16 v[54:57], v[214:217], v[174:177], v[54:57]
	v_mfma_f32_16x16x32_bf16 v[50:53], v[222:225], v[174:177], v[50:53]
	v_mfma_f32_16x16x32_bf16 v[38:41], v[214:217], v[190:193], v[38:41]
	v_mfma_f32_16x16x32_bf16 v[34:37], v[222:225], v[190:193], v[34:37]
	v_mfma_f32_16x16x32_bf16 v[22:25], v[214:217], v[198:201], v[22:25]
	v_mfma_f32_16x16x32_bf16 v[18:21], v[222:225], v[198:201], v[18:21]
	v_mfma_f32_16x16x32_bf16 v[6:9], v[214:217], v[206:209], v[6:9]
	v_mfma_f32_16x16x32_bf16 v[2:5], v[222:225], v[206:209], v[2:5]
	v_mfma_f32_16x16x32_bf16 v[54:57], v[218:221], v[186:189], v[54:57]
	v_mfma_f32_16x16x32_bf16 v[50:53], v[226:229], v[186:189], v[50:53]
	v_mfma_f32_16x16x32_bf16 v[38:41], v[218:221], v[194:197], v[38:41]
	v_mfma_f32_16x16x32_bf16 v[34:37], v[226:229], v[194:197], v[34:37]
	v_mfma_f32_16x16x32_bf16 v[22:25], v[218:221], v[202:205], v[22:25]
	v_mfma_f32_16x16x32_bf16 v[18:21], v[226:229], v[202:205], v[18:21]
	v_mfma_f32_16x16x32_bf16 v[6:9], v[218:221], v[210:213], v[6:9]
	v_mfma_f32_16x16x32_bf16 v[2:5], v[226:229], v[210:213], v[2:5]
	s_setprio 0
	s_add_i32 s26, 16, 0x18000
	v_add_u32_e32 v151, s26, v148
	s_barrier
	ds_read_b128 v[134:137], v151
	ds_read_b128 v[162:165], v151 offset:1024
	ds_read_b128 v[166:169], v151 offset:2048
	ds_read_b128 v[170:173], v151 offset:3072
	s_add_u32 s12, s12, 0x80000
	s_addc_u32 s13, s13, 0
	s_mov_b32 m0, s40
	v_lshl_add_u64 v[214:215], s[12:13], 0, v[154:155]
	ds_read_b128 v[174:177], v150 offset:32768
	ds_read_b128 v[186:189], v150 offset:33792
	ds_read_b128 v[190:193], v150 offset:34816
	ds_read_b128 v[194:197], v150 offset:35840
	ds_read_b128 v[198:201], v150 offset:36864
	ds_read_b128 v[202:205], v150 offset:37888
	ds_read_b128 v[206:209], v150 offset:38912
	ds_read_b128 v[210:213], v150 offset:39936
	global_load_lds_dwordx4 v[214:215], off
	v_lshl_add_u64 v[214:215], s[12:13], 0, v[158:159]
	s_mov_b32 m0, s41
	s_nop 0
	global_load_lds_dwordx4 v[214:215], off
	s_waitcnt lgkmcnt(8)
	s_barrier
	s_waitcnt lgkmcnt(0)
	s_setprio 1
	s_waitcnt lgkmcnt(0)
	v_mfma_f32_16x16x32_bf16 v[126:129], v[134:137], v[174:177], v[126:129]
	v_mfma_f32_16x16x32_bf16 v[122:125], v[166:169], v[174:177], v[122:125]
	v_mfma_f32_16x16x32_bf16 v[110:113], v[134:137], v[190:193], v[110:113]
	v_mfma_f32_16x16x32_bf16 v[106:109], v[166:169], v[190:193], v[106:109]
	v_mfma_f32_16x16x32_bf16 v[94:97], v[134:137], v[198:201], v[94:97]
	v_mfma_f32_16x16x32_bf16 v[90:93], v[166:169], v[198:201], v[90:93]
	v_mfma_f32_16x16x32_bf16 v[78:81], v[134:137], v[206:209], v[78:81]
	v_mfma_f32_16x16x32_bf16 v[74:77], v[166:169], v[206:209], v[74:77]
	v_mfma_f32_16x16x32_bf16 v[126:129], v[162:165], v[186:189], v[126:129]
	v_mfma_f32_16x16x32_bf16 v[122:125], v[170:173], v[186:189], v[122:125]
	v_mfma_f32_16x16x32_bf16 v[110:113], v[162:165], v[194:197], v[110:113]
	v_mfma_f32_16x16x32_bf16 v[106:109], v[170:173], v[194:197], v[106:109]
	v_mfma_f32_16x16x32_bf16 v[94:97], v[162:165], v[202:205], v[94:97]
	v_mfma_f32_16x16x32_bf16 v[90:93], v[170:173], v[202:205], v[90:93]
	v_mfma_f32_16x16x32_bf16 v[78:81], v[162:165], v[210:213], v[78:81]
	v_mfma_f32_16x16x32_bf16 v[74:77], v[170:173], v[210:213], v[74:77]
	s_setprio 0
	s_barrier
	s_add_i32 s12, 16, 0x1c000
	s_add_i32 s13, s26, s18
	v_add_u32_e32 v151, s12, v148
	v_lshl_add_u64 v[152:153], v[152:153], 0, s[92:93]
	s_mov_b32 m0, s13
	ds_read_b128 v[214:217], v151
	ds_read_b128 v[218:221], v151 offset:1024
	ds_read_b128 v[222:225], v151 offset:2048
	ds_read_b128 v[226:229], v151 offset:3072
	global_load_lds_dwordx4 v[152:153], off
	v_lshl_add_u64 v[152:153], v[178:179], 0, s[92:93]
	s_add_i32 m0, s13, 0x2000
	s_nop 0
	global_load_lds_dwordx4 v[152:153], off
	s_barrier
	s_waitcnt lgkmcnt(0)
	s_setprio 1
	s_waitcnt lgkmcnt(0)
	v_mfma_f32_16x16x32_bf16 v[118:121], v[214:217], v[174:177], v[118:121]
	v_mfma_f32_16x16x32_bf16 v[114:117], v[222:225], v[174:177], v[114:117]
	v_mfma_f32_16x16x32_bf16 v[102:105], v[214:217], v[190:193], v[102:105]
	v_mfma_f32_16x16x32_bf16 v[98:101], v[222:225], v[190:193], v[98:101]
	v_mfma_f32_16x16x32_bf16 v[86:89], v[214:217], v[198:201], v[86:89]
	v_mfma_f32_16x16x32_bf16 v[82:85], v[222:225], v[198:201], v[82:85]
	v_mfma_f32_16x16x32_bf16 v[70:73], v[214:217], v[206:209], v[70:73]
	v_mfma_f32_16x16x32_bf16 v[66:69], v[222:225], v[206:209], v[66:69]
	v_mfma_f32_16x16x32_bf16 v[118:121], v[218:221], v[186:189], v[118:121]
	v_mfma_f32_16x16x32_bf16 v[114:117], v[226:229], v[186:189], v[114:117]
	v_mfma_f32_16x16x32_bf16 v[102:105], v[218:221], v[194:197], v[102:105]
	v_mfma_f32_16x16x32_bf16 v[98:101], v[226:229], v[194:197], v[98:101]
	v_mfma_f32_16x16x32_bf16 v[86:89], v[218:221], v[202:205], v[86:89]
	v_mfma_f32_16x16x32_bf16 v[82:85], v[226:229], v[202:205], v[82:85]
	v_mfma_f32_16x16x32_bf16 v[70:73], v[218:221], v[210:213], v[70:73]
	v_mfma_f32_16x16x32_bf16 v[66:69], v[226:229], v[210:213], v[66:69]
	s_setprio 0
	s_mov_b32 m0, s19
	v_lshl_add_u64 v[152:153], v[230:231], 0, s[92:93]
	s_barrier
	ds_read_b128 v[174:177], v150 offset:49152
	ds_read_b128 v[186:189], v150 offset:50176
	ds_read_b128 v[190:193], v150 offset:51200
	ds_read_b128 v[194:197], v150 offset:52224
	ds_read_b128 v[198:201], v150 offset:53248
	ds_read_b128 v[202:205], v150 offset:54272
	ds_read_b128 v[206:209], v150 offset:55296
	ds_read_b128 v[210:213], v150 offset:56320
	global_load_lds_dwordx4 v[152:153], off
	v_lshl_add_u64 v[152:153], v[242:243], 0, s[92:93]
	s_mov_b32 m0, s64
	s_nop 0
	global_load_lds_dwordx4 v[152:153], off
	s_barrier
	s_waitcnt lgkmcnt(0)
	s_setprio 1
	s_waitcnt lgkmcnt(0)
	v_mfma_f32_16x16x32_bf16 v[62:65], v[134:137], v[174:177], v[62:65]
	v_mfma_f32_16x16x32_bf16 v[58:61], v[166:169], v[174:177], v[58:61]
	v_mfma_f32_16x16x32_bf16 v[46:49], v[134:137], v[190:193], v[46:49]
	v_mfma_f32_16x16x32_bf16 v[42:45], v[166:169], v[190:193], v[42:45]
	v_mfma_f32_16x16x32_bf16 v[30:33], v[134:137], v[198:201], v[30:33]
	v_mfma_f32_16x16x32_bf16 v[26:29], v[166:169], v[198:201], v[26:29]
	v_mfma_f32_16x16x32_bf16 v[14:17], v[134:137], v[206:209], v[14:17]
	v_mfma_f32_16x16x32_bf16 v[10:13], v[166:169], v[206:209], v[10:13]
	v_mfma_f32_16x16x32_bf16 v[62:65], v[162:165], v[186:189], v[62:65]
	v_mfma_f32_16x16x32_bf16 v[58:61], v[170:173], v[186:189], v[58:61]
	v_mfma_f32_16x16x32_bf16 v[46:49], v[162:165], v[194:197], v[46:49]
	v_mfma_f32_16x16x32_bf16 v[42:45], v[170:173], v[194:197], v[42:45]
	v_mfma_f32_16x16x32_bf16 v[30:33], v[162:165], v[202:205], v[30:33]
	v_mfma_f32_16x16x32_bf16 v[26:29], v[170:173], v[202:205], v[26:29]
	v_mfma_f32_16x16x32_bf16 v[14:17], v[162:165], v[210:213], v[14:17]
	v_mfma_f32_16x16x32_bf16 v[10:13], v[170:173], v[210:213], v[10:13]
	s_setprio 0
	s_barrier
	s_add_u32 s4, s4, 0x80080
	s_addc_u32 s5, s5, 0
	s_add_i32 s12, s12, s18
	v_lshl_add_u64 v[134:135], s[4:5], 0, v[156:157]
	s_mov_b32 m0, s12
	s_nop 0
	global_load_lds_dwordx4 v[134:135], off
	v_lshl_add_u64 v[134:135], s[4:5], 0, v[160:161]
	s_add_i32 m0, s12, 0x2000
	s_nop 0
	global_load_lds_dwordx4 v[134:135], off
	s_waitcnt vmcnt(6)
	s_barrier
	s_setprio 1
	v_mfma_f32_16x16x32_bf16 v[54:57], v[214:217], v[174:177], v[54:57]
	v_mfma_f32_16x16x32_bf16 v[50:53], v[222:225], v[174:177], v[50:53]
	v_mfma_f32_16x16x32_bf16 v[38:41], v[214:217], v[190:193], v[38:41]
	v_mfma_f32_16x16x32_bf16 v[34:37], v[222:225], v[190:193], v[34:37]
	v_mfma_f32_16x16x32_bf16 v[22:25], v[214:217], v[198:201], v[22:25]
	v_mfma_f32_16x16x32_bf16 v[18:21], v[222:225], v[198:201], v[18:21]
	v_mfma_f32_16x16x32_bf16 v[6:9], v[214:217], v[206:209], v[6:9]
	v_mfma_f32_16x16x32_bf16 v[2:5], v[222:225], v[206:209], v[2:5]
	v_mfma_f32_16x16x32_bf16 v[54:57], v[218:221], v[186:189], v[54:57]
	v_mfma_f32_16x16x32_bf16 v[50:53], v[226:229], v[186:189], v[50:53]
	v_mfma_f32_16x16x32_bf16 v[38:41], v[218:221], v[194:197], v[38:41]
	v_mfma_f32_16x16x32_bf16 v[34:37], v[226:229], v[194:197], v[34:37]
	v_mfma_f32_16x16x32_bf16 v[22:25], v[218:221], v[202:205], v[22:25]
	v_mfma_f32_16x16x32_bf16 v[18:21], v[226:229], v[202:205], v[18:21]
	v_mfma_f32_16x16x32_bf16 v[6:9], v[218:221], v[210:213], v[6:9]
	v_mfma_f32_16x16x32_bf16 v[2:5], v[226:229], v[210:213], v[2:5]
	s_setprio 0
	s_add_i32 s47, s47, 2
	s_add_u32 s0, s0, 0x100
	s_addc_u32 s1, s1, 0
	s_add_u32 s30, s30, 0x100
	s_addc_u32 s45, s45, 0
	s_cmp_gt_u32 s47, 29
	s_barrier
	s_cbranch_scc0 .LBB0_104
	v_lshl_add_u32 v134, s46, 8, v147
	v_ashrrev_i32_e32 v135, 31, v134
	v_readlane_b32 s4, v252, 24
	v_lshlrev_b64 v[162:163], 5, v[134:135]
	v_readlane_b32 s5, v252, 25
	v_lshlrev_b64 v[152:153], 12, v[134:135]
	s_mov_b32 s11, 0xf800000
	v_lshl_add_u64 v[166:167], s[4:5], 0, v[162:163]
	global_load_dwordx4 v[162:165], v[166:167], off
	s_nop 0
	global_load_dwordx4 v[166:169], v[166:167], off offset:16
	v_or_b32_e32 v176, 16, v134
	v_ashrrev_i32_e32 v177, 31, v176
	v_lshlrev_b64 v[176:177], 5, v[176:177]
	v_lshl_add_u64 v[176:177], s[4:5], 0, v[176:177]
	global_load_dwordx4 v[186:189], v[176:177], off
	global_load_dwordx4 v[190:193], v[176:177], off offset:16
	v_or_b32_e32 v176, 32, v134
	v_ashrrev_i32_e32 v177, 31, v176
	v_lshlrev_b64 v[176:177], 5, v[176:177]
	v_lshl_add_u64 v[176:177], s[4:5], 0, v[176:177]
	global_load_dwordx4 v[194:197], v[176:177], off
	global_load_dwordx4 v[198:201], v[176:177], off offset:16
	v_or_b32_e32 v176, 48, v134
	v_ashrrev_i32_e32 v177, 31, v176
	v_lshlrev_b64 v[176:177], 5, v[176:177]
	v_lshl_add_u64 v[176:177], s[4:5], 0, v[176:177]
	global_load_dwordx4 v[202:205], v[176:177], off
	global_load_dwordx4 v[206:209], v[176:177], off offset:16
	v_add_u32_e32 v176, 0x80, v134
	v_ashrrev_i32_e32 v177, 31, v176
	v_lshlrev_b64 v[176:177], 5, v[176:177]
	v_lshl_add_u64 v[176:177], s[4:5], 0, v[176:177]
	global_load_dwordx4 v[210:213], v[176:177], off
	global_load_dwordx4 v[214:217], v[176:177], off offset:16
	v_add_u32_e32 v176, 0x90, v134
	v_ashrrev_i32_e32 v177, 31, v176
	v_lshlrev_b64 v[176:177], 5, v[176:177]
	v_lshl_add_u64 v[176:177], s[4:5], 0, v[176:177]
	global_load_dwordx4 v[218:221], v[176:177], off
	global_load_dwordx4 v[222:225], v[176:177], off offset:16
	v_add_u32_e32 v176, 0xa0, v134
	v_ashrrev_i32_e32 v177, 31, v176
	v_lshlrev_b64 v[176:177], 5, v[176:177]
	v_lshl_add_u64 v[176:177], s[4:5], 0, v[176:177]
	global_load_dwordx4 v[226:229], v[176:177], off
	global_load_dwordx4 v[172:175], v[176:177], off offset:16
	v_lshl_or_b32 v136, s2, 8, v149
	v_readlane_b32 s2, v252, 20
	v_ashrrev_i32_e32 v137, 31, v136
	v_readlane_b32 s3, v252, 21
	v_lshlrev_b64 v[136:137], 1, v[136:137]
	s_mov_b64 s[12:13], s[28:29]
	v_lshl_add_u64 v[152:153], s[2:3], 0, v[152:153]
	v_lshl_add_u64 v[152:153], v[152:153], 0, v[136:137]
	s_mov_b32 s16, 0x1a000
	s_mov_b64 s[28:29], 0
	s_waitcnt vmcnt(0)
	v_mov_b32_e32 v170, v162
	v_mov_b32_e32 v171, v166
	v_mov_b32_e32 v166, v163
	v_pk_add_f32 v[162:163], v[170:171], v[166:167]
	v_mov_b32_e32 v166, v164
	v_mov_b32_e32 v167, v168
	v_mov_b32_e32 v168, v165
	v_pk_add_f32 v[164:165], v[166:167], v[168:169]
	s_nop 0
	v_pk_add_f32 v[162:163], v[162:163], v[164:165]
	s_nop 0
	v_add_f32_e32 v135, v162, v163
	v_fmamk_f32 v135, v135, 0x3a000000, v233
	v_cmp_gt_f32_e32 vcc, s11, v135
	v_mul_f32_e32 v151, 0x4f800000, v135
	s_nop 0
	v_cndmask_b32_e32 v135, v135, v151, vcc
	v_sqrt_f32_e32 v151, v135
	s_nop 0
	v_add_u32_e32 v162, -1, v151
	v_fma_f32 v163, -v162, v151, v135
	v_cmp_ge_f32_e64 s[46:47], 0, v163
	v_add_u32_e32 v163, 1, v151
	s_nop 0
	v_cndmask_b32_e64 v162, v151, v162, s[46:47]
	v_fma_f32 v151, -v163, v151, v135
	v_cmp_lt_f32_e64 s[46:47], 0, v151
	s_nop 1
	v_cndmask_b32_e64 v151, v162, v163, s[46:47]
	v_mul_f32_e32 v162, 0x37800000, v151
	v_cndmask_b32_e32 v151, v151, v162, vcc
	v_cmp_class_f32_e32 vcc, v135, v234
	s_nop 1
	v_cndmask_b32_e32 v135, v151, v135, vcc
	v_div_scale_f32 v151, s[0:1], v135, v135, 1.0
	v_rcp_f32_e32 v162, v151
	s_nop 0
	v_fma_f32 v163, -v151, v162, 1.0
	v_fmac_f32_e32 v162, v163, v162
	v_div_scale_f32 v163, vcc, 1.0, v135, 1.0
	v_mul_f32_e32 v164, v163, v162
	v_fma_f32 v165, -v151, v164, v163
	v_fmac_f32_e32 v164, v165, v162
	v_fma_f32 v151, -v151, v164, v163
	v_div_fmas_f32 v151, v151, v162, v164
	v_div_fixup_f32 v162, v151, v135, 1.0
	v_pk_mul_f32 v[128:129], v[128:129], v[162:163] op_sel_hi:[1,0]
	v_pk_mul_f32 v[126:127], v[126:127], v[162:163] op_sel_hi:[1,0]
	v_pk_mul_f32 v[164:165], v[124:125], v[162:163] op_sel_hi:[1,0]
	v_pk_mul_f32 v[124:125], v[122:123], v[162:163] op_sel_hi:[1,0]
	v_cvt_pk_bf16_f32 v122, v126, v127
	v_cvt_pk_bf16_f32 v123, v128, v129
	v_cvt_pk_bf16_f32 v124, v124, v125
	v_cvt_pk_bf16_f32 v125, v164, v165
	global_store_dwordx4 v[152:153], v[122:125], off
	v_pk_mul_f32 v[120:121], v[120:121], v[162:163] op_sel_hi:[1,0]
	v_pk_mul_f32 v[118:119], v[118:119], v[162:163] op_sel_hi:[1,0]
	v_pk_mul_f32 v[122:123], v[116:117], v[162:163] op_sel_hi:[1,0]
	v_pk_mul_f32 v[116:117], v[114:115], v[162:163] op_sel_hi:[1,0]
	v_cvt_pk_bf16_f32 v114, v118, v119
	v_cvt_pk_bf16_f32 v115, v120, v121
	v_cvt_pk_bf16_f32 v116, v116, v117
	v_cvt_pk_bf16_f32 v117, v122, v123
	global_store_dwordx4 v[152:153], v[114:117], off offset:256
	s_nop 1
	v_or_b32_e32 v116, 16, v134
	v_ashrrev_i32_e32 v117, 31, v116
	v_lshlrev_b64 v[114:115], 12, v[116:117]
	v_lshlrev_b64 v[116:117], 5, v[116:117]
	v_lshl_add_u64 v[120:121], s[4:5], 0, v[116:117]
	s_nop 0
	v_lshl_add_u64 v[114:115], s[2:3], 0, v[114:115]
	v_lshl_add_u64 v[114:115], v[114:115], 0, v[136:137]
	v_mov_b32_e32 v116, v186
	v_mov_b32_e32 v117, v187
	v_mov_b32_e32 v118, v188
	v_mov_b32_e32 v119, v189
	v_mov_b32_e32 v120, v190
	v_mov_b32_e32 v121, v191
	v_mov_b32_e32 v122, v192
	v_mov_b32_e32 v123, v193
	v_add_u32_e32 v176, 0xb0, v134
	v_ashrrev_i32_e32 v177, 31, v176
	v_lshlrev_b64 v[176:177], 5, v[176:177]
	v_lshl_add_u64 v[176:177], s[4:5], 0, v[176:177]
	global_load_dwordx4 v[186:189], v[176:177], off
	global_load_dwordx4 v[190:193], v[176:177], off offset:16
	v_mov_b32_e32 v124, v116
	v_mov_b32_e32 v125, v120
	v_mov_b32_e32 v120, v117
	v_pk_add_f32 v[116:117], v[124:125], v[120:121]
	v_mov_b32_e32 v120, v118
	v_mov_b32_e32 v121, v122
	v_mov_b32_e32 v122, v119
	v_pk_add_f32 v[118:119], v[120:121], v[122:123]
	s_nop 0
	v_pk_add_f32 v[116:117], v[116:117], v[118:119]
	s_nop 0
	v_add_f32_e32 v116, v116, v117
	v_fmamk_f32 v116, v116, 0x3a000000, v233
	v_cmp_gt_f32_e32 vcc, s11, v116
	v_mul_f32_e32 v117, 0x4f800000, v116
	s_nop 0
	v_cndmask_b32_e32 v116, v116, v117, vcc
	v_sqrt_f32_e32 v117, v116
	s_nop 0
	v_add_u32_e32 v118, -1, v117
	v_fma_f32 v119, -v118, v117, v116
	v_cmp_ge_f32_e64 s[46:47], 0, v119
	v_add_u32_e32 v119, 1, v117
	s_nop 0
	v_cndmask_b32_e64 v118, v117, v118, s[46:47]
	v_fma_f32 v117, -v119, v117, v116
	v_cmp_lt_f32_e64 s[46:47], 0, v117
	s_nop 1
	v_cndmask_b32_e64 v117, v118, v119, s[46:47]
	v_mul_f32_e32 v118, 0x37800000, v117
	v_cndmask_b32_e32 v117, v117, v118, vcc
	v_cmp_class_f32_e32 vcc, v116, v234
	s_nop 1
	v_cndmask_b32_e32 v116, v117, v116, vcc
	v_div_scale_f32 v117, s[0:1], v116, v116, 1.0
	v_rcp_f32_e32 v118, v117
	s_nop 0
	v_fma_f32 v119, -v117, v118, 1.0
	v_fmac_f32_e32 v118, v119, v118
	v_div_scale_f32 v119, vcc, 1.0, v116, 1.0
	v_mul_f32_e32 v120, v119, v118
	v_fma_f32 v121, -v117, v120, v119
	v_fmac_f32_e32 v120, v121, v118
	v_fma_f32 v117, -v117, v120, v119
	v_div_fmas_f32 v117, v117, v118, v120
	v_div_fixup_f32 v116, v117, v116, 1.0
	v_pk_mul_f32 v[112:113], v[112:113], v[116:117] op_sel_hi:[1,0]
	v_pk_mul_f32 v[110:111], v[110:111], v[116:117] op_sel_hi:[1,0]
	v_pk_mul_f32 v[118:119], v[108:109], v[116:117] op_sel_hi:[1,0]
	v_pk_mul_f32 v[108:109], v[106:107], v[116:117] op_sel_hi:[1,0]
	v_cvt_pk_bf16_f32 v106, v110, v111
	v_cvt_pk_bf16_f32 v107, v112, v113
	v_cvt_pk_bf16_f32 v108, v108, v109
	v_cvt_pk_bf16_f32 v109, v118, v119
	global_store_dwordx4 v[114:115], v[106:109], off
	v_pk_mul_f32 v[104:105], v[104:105], v[116:117] op_sel_hi:[1,0]
	v_pk_mul_f32 v[102:103], v[102:103], v[116:117] op_sel_hi:[1,0]
	v_pk_mul_f32 v[106:107], v[100:101], v[116:117] op_sel_hi:[1,0]
	v_pk_mul_f32 v[100:101], v[98:99], v[116:117] op_sel_hi:[1,0]
	v_cvt_pk_bf16_f32 v98, v102, v103
	v_cvt_pk_bf16_f32 v99, v104, v105
	v_cvt_pk_bf16_f32 v100, v100, v101
	v_cvt_pk_bf16_f32 v101, v106, v107
	global_store_dwordx4 v[114:115], v[98:101], off offset:256
	s_nop 1
	v_or_b32_e32 v100, 32, v134
	v_ashrrev_i32_e32 v101, 31, v100
	v_lshlrev_b64 v[98:99], 12, v[100:101]
	v_lshlrev_b64 v[100:101], 5, v[100:101]
	v_lshl_add_u64 v[104:105], s[4:5], 0, v[100:101]
	s_nop 0
	v_lshl_add_u64 v[98:99], s[2:3], 0, v[98:99]
	v_lshl_add_u64 v[98:99], v[98:99], 0, v[136:137]
	v_mov_b32_e32 v100, v194
	v_mov_b32_e32 v101, v195
	v_mov_b32_e32 v102, v196
	v_mov_b32_e32 v103, v197
	v_mov_b32_e32 v104, v198
	v_mov_b32_e32 v105, v199
	v_mov_b32_e32 v106, v200
	v_mov_b32_e32 v107, v201
	v_mov_b32_e32 v108, v100
	v_mov_b32_e32 v109, v104
	v_mov_b32_e32 v104, v101
	v_pk_add_f32 v[100:101], v[108:109], v[104:105]
	v_mov_b32_e32 v104, v102
	v_mov_b32_e32 v105, v106
	v_mov_b32_e32 v106, v103
	v_pk_add_f32 v[102:103], v[104:105], v[106:107]
	s_nop 0
	v_pk_add_f32 v[100:101], v[100:101], v[102:103]
	s_nop 0
	v_add_f32_e32 v100, v100, v101
	v_fmamk_f32 v100, v100, 0x3a000000, v233
	v_cmp_gt_f32_e32 vcc, s11, v100
	v_mul_f32_e32 v101, 0x4f800000, v100
	s_nop 0
	v_cndmask_b32_e32 v100, v100, v101, vcc
	v_sqrt_f32_e32 v101, v100
	s_nop 0
	v_add_u32_e32 v102, -1, v101
	v_fma_f32 v103, -v102, v101, v100
	v_cmp_ge_f32_e64 s[46:47], 0, v103
	v_add_u32_e32 v103, 1, v101
	s_nop 0
	v_cndmask_b32_e64 v102, v101, v102, s[46:47]
	v_fma_f32 v101, -v103, v101, v100
	v_cmp_lt_f32_e64 s[46:47], 0, v101
	s_nop 1
	v_cndmask_b32_e64 v101, v102, v103, s[46:47]
	v_mul_f32_e32 v102, 0x37800000, v101
	v_cndmask_b32_e32 v101, v101, v102, vcc
	v_cmp_class_f32_e32 vcc, v100, v234
	s_nop 1
	v_cndmask_b32_e32 v100, v101, v100, vcc
	v_div_scale_f32 v101, s[0:1], v100, v100, 1.0
	v_rcp_f32_e32 v102, v101
	s_nop 0
	v_fma_f32 v103, -v101, v102, 1.0
	v_fmac_f32_e32 v102, v103, v102
	v_div_scale_f32 v103, vcc, 1.0, v100, 1.0
	v_mul_f32_e32 v104, v103, v102
	v_fma_f32 v105, -v101, v104, v103
	v_fmac_f32_e32 v104, v105, v102
	v_fma_f32 v101, -v101, v104, v103
	v_div_fmas_f32 v101, v101, v102, v104
	v_div_fixup_f32 v100, v101, v100, 1.0
	v_pk_mul_f32 v[96:97], v[96:97], v[100:101] op_sel_hi:[1,0]
	v_pk_mul_f32 v[94:95], v[94:95], v[100:101] op_sel_hi:[1,0]
	v_pk_mul_f32 v[102:103], v[92:93], v[100:101] op_sel_hi:[1,0]
	v_pk_mul_f32 v[92:93], v[90:91], v[100:101] op_sel_hi:[1,0]
	v_cvt_pk_bf16_f32 v90, v94, v95
	v_cvt_pk_bf16_f32 v91, v96, v97
	v_cvt_pk_bf16_f32 v92, v92, v93
	v_cvt_pk_bf16_f32 v93, v102, v103
	global_store_dwordx4 v[98:99], v[90:93], off
	v_pk_mul_f32 v[88:89], v[88:89], v[100:101] op_sel_hi:[1,0]
	v_pk_mul_f32 v[86:87], v[86:87], v[100:101] op_sel_hi:[1,0]
	v_pk_mul_f32 v[90:91], v[84:85], v[100:101] op_sel_hi:[1,0]
	v_pk_mul_f32 v[84:85], v[82:83], v[100:101] op_sel_hi:[1,0]
	v_cvt_pk_bf16_f32 v82, v86, v87
	v_cvt_pk_bf16_f32 v83, v88, v89
	v_cvt_pk_bf16_f32 v84, v84, v85
	v_cvt_pk_bf16_f32 v85, v90, v91
	global_store_dwordx4 v[98:99], v[82:85], off offset:256
	s_nop 1
	v_or_b32_e32 v84, 48, v134
	v_ashrrev_i32_e32 v85, 31, v84
	v_lshlrev_b64 v[82:83], 12, v[84:85]
	v_lshlrev_b64 v[84:85], 5, v[84:85]
	v_lshl_add_u64 v[88:89], s[4:5], 0, v[84:85]
	s_nop 0
	v_lshl_add_u64 v[82:83], s[2:3], 0, v[82:83]
	v_lshl_add_u64 v[82:83], v[82:83], 0, v[136:137]
	v_mov_b32_e32 v84, v202
	v_mov_b32_e32 v85, v203
	v_mov_b32_e32 v86, v204
	v_mov_b32_e32 v87, v205
	v_mov_b32_e32 v88, v206
	v_mov_b32_e32 v89, v207
	v_mov_b32_e32 v90, v208
	v_mov_b32_e32 v91, v209
	v_mov_b32_e32 v92, v84
	v_mov_b32_e32 v93, v88
	v_mov_b32_e32 v88, v85
	v_pk_add_f32 v[84:85], v[92:93], v[88:89]
	v_mov_b32_e32 v88, v86
	v_mov_b32_e32 v89, v90
	v_mov_b32_e32 v90, v87
	v_pk_add_f32 v[86:87], v[88:89], v[90:91]
	s_nop 0
	v_pk_add_f32 v[84:85], v[84:85], v[86:87]
	s_nop 0
	v_add_f32_e32 v84, v84, v85
	v_fmamk_f32 v84, v84, 0x3a000000, v233
	v_cmp_gt_f32_e32 vcc, s11, v84
	v_mul_f32_e32 v85, 0x4f800000, v84
	s_nop 0
	v_cndmask_b32_e32 v84, v84, v85, vcc
	v_sqrt_f32_e32 v85, v84
	s_nop 0
	v_add_u32_e32 v86, -1, v85
	v_fma_f32 v87, -v86, v85, v84
	v_cmp_ge_f32_e64 s[46:47], 0, v87
	v_add_u32_e32 v87, 1, v85
	s_nop 0
	v_cndmask_b32_e64 v86, v85, v86, s[46:47]
	v_fma_f32 v85, -v87, v85, v84
	v_cmp_lt_f32_e64 s[46:47], 0, v85
	s_nop 1
	v_cndmask_b32_e64 v85, v86, v87, s[46:47]
	v_mul_f32_e32 v86, 0x37800000, v85
	v_cndmask_b32_e32 v85, v85, v86, vcc
	v_cmp_class_f32_e32 vcc, v84, v234
	s_nop 1
	v_cndmask_b32_e32 v84, v85, v84, vcc
	v_div_scale_f32 v85, s[0:1], v84, v84, 1.0
	v_rcp_f32_e32 v86, v85
	s_nop 0
	v_fma_f32 v87, -v85, v86, 1.0
	v_fmac_f32_e32 v86, v87, v86
	v_div_scale_f32 v87, vcc, 1.0, v84, 1.0
	v_mul_f32_e32 v88, v87, v86
	v_fma_f32 v89, -v85, v88, v87
	v_fmac_f32_e32 v88, v89, v86
	v_fma_f32 v85, -v85, v88, v87
	v_div_fmas_f32 v85, v85, v86, v88
	v_div_fixup_f32 v84, v85, v84, 1.0
	v_pk_mul_f32 v[80:81], v[80:81], v[84:85] op_sel_hi:[1,0]
	v_pk_mul_f32 v[78:79], v[78:79], v[84:85] op_sel_hi:[1,0]
	v_pk_mul_f32 v[86:87], v[76:77], v[84:85] op_sel_hi:[1,0]
	v_pk_mul_f32 v[76:77], v[74:75], v[84:85] op_sel_hi:[1,0]
	v_cvt_pk_bf16_f32 v74, v78, v79
	v_cvt_pk_bf16_f32 v75, v80, v81
	v_cvt_pk_bf16_f32 v76, v76, v77
	v_cvt_pk_bf16_f32 v77, v86, v87
	global_store_dwordx4 v[82:83], v[74:77], off
	v_pk_mul_f32 v[72:73], v[72:73], v[84:85] op_sel_hi:[1,0]
	v_pk_mul_f32 v[70:71], v[70:71], v[84:85] op_sel_hi:[1,0]
	v_pk_mul_f32 v[74:75], v[68:69], v[84:85] op_sel_hi:[1,0]
	v_pk_mul_f32 v[68:69], v[66:67], v[84:85] op_sel_hi:[1,0]
	v_cvt_pk_bf16_f32 v66, v70, v71
	v_cvt_pk_bf16_f32 v67, v72, v73
	v_cvt_pk_bf16_f32 v68, v68, v69
	v_cvt_pk_bf16_f32 v69, v74, v75
	global_store_dwordx4 v[82:83], v[66:69], off offset:256
	s_nop 1
	v_add_u32_e32 v68, 0x80, v134
	v_ashrrev_i32_e32 v69, 31, v68
	v_lshlrev_b64 v[66:67], 12, v[68:69]
	v_lshlrev_b64 v[68:69], 5, v[68:69]
	v_lshl_add_u64 v[72:73], s[4:5], 0, v[68:69]
	s_nop 0
	v_lshl_add_u64 v[66:67], s[2:3], 0, v[66:67]
	v_lshl_add_u64 v[66:67], v[66:67], 0, v[136:137]
	v_mov_b32_e32 v68, v210
	v_mov_b32_e32 v69, v211
	v_mov_b32_e32 v70, v212
	v_mov_b32_e32 v71, v213
	v_mov_b32_e32 v72, v214
	v_mov_b32_e32 v73, v215
	v_mov_b32_e32 v74, v216
	v_mov_b32_e32 v75, v217
	v_mov_b32_e32 v76, v68
	v_mov_b32_e32 v77, v72
	v_mov_b32_e32 v72, v69
	v_pk_add_f32 v[68:69], v[76:77], v[72:73]
	v_mov_b32_e32 v72, v70
	v_mov_b32_e32 v73, v74
	v_mov_b32_e32 v74, v71
	v_pk_add_f32 v[70:71], v[72:73], v[74:75]
	s_nop 0
	v_pk_add_f32 v[68:69], v[68:69], v[70:71]
	s_nop 0
	v_add_f32_e32 v68, v68, v69
	v_fmamk_f32 v68, v68, 0x3a000000, v233
	v_cmp_gt_f32_e32 vcc, s11, v68
	v_mul_f32_e32 v69, 0x4f800000, v68
	s_nop 0
	v_cndmask_b32_e32 v68, v68, v69, vcc
	v_sqrt_f32_e32 v69, v68
	s_nop 0
	v_add_u32_e32 v70, -1, v69
	v_fma_f32 v71, -v70, v69, v68
	v_cmp_ge_f32_e64 s[46:47], 0, v71
	v_add_u32_e32 v71, 1, v69
	s_nop 0
	v_cndmask_b32_e64 v70, v69, v70, s[46:47]
	v_fma_f32 v69, -v71, v69, v68
	v_cmp_lt_f32_e64 s[46:47], 0, v69
	s_nop 1
	v_cndmask_b32_e64 v69, v70, v71, s[46:47]
	v_mul_f32_e32 v70, 0x37800000, v69
	v_cndmask_b32_e32 v69, v69, v70, vcc
	v_cmp_class_f32_e32 vcc, v68, v234
	s_nop 1
	v_cndmask_b32_e32 v68, v69, v68, vcc
	v_div_scale_f32 v69, s[0:1], v68, v68, 1.0
	v_rcp_f32_e32 v70, v69
	s_nop 0
	v_fma_f32 v71, -v69, v70, 1.0
	v_fmac_f32_e32 v70, v71, v70
	v_div_scale_f32 v71, vcc, 1.0, v68, 1.0
	v_mul_f32_e32 v72, v71, v70
	v_fma_f32 v73, -v69, v72, v71
	v_fmac_f32_e32 v72, v73, v70
	v_fma_f32 v69, -v69, v72, v71
	v_div_fmas_f32 v69, v69, v70, v72
	v_div_fixup_f32 v68, v69, v68, 1.0
	v_pk_mul_f32 v[64:65], v[64:65], v[68:69] op_sel_hi:[1,0]
	v_pk_mul_f32 v[62:63], v[62:63], v[68:69] op_sel_hi:[1,0]
	v_pk_mul_f32 v[70:71], v[60:61], v[68:69] op_sel_hi:[1,0]
	v_pk_mul_f32 v[60:61], v[58:59], v[68:69] op_sel_hi:[1,0]
	v_cvt_pk_bf16_f32 v58, v62, v63
	v_cvt_pk_bf16_f32 v59, v64, v65
	v_cvt_pk_bf16_f32 v60, v60, v61
	v_cvt_pk_bf16_f32 v61, v70, v71
	global_store_dwordx4 v[66:67], v[58:61], off
	v_pk_mul_f32 v[56:57], v[56:57], v[68:69] op_sel_hi:[1,0]
	v_pk_mul_f32 v[54:55], v[54:55], v[68:69] op_sel_hi:[1,0]
	v_pk_mul_f32 v[58:59], v[52:53], v[68:69] op_sel_hi:[1,0]
	v_pk_mul_f32 v[52:53], v[50:51], v[68:69] op_sel_hi:[1,0]
	v_cvt_pk_bf16_f32 v50, v54, v55
	v_cvt_pk_bf16_f32 v51, v56, v57
	v_cvt_pk_bf16_f32 v52, v52, v53
	v_cvt_pk_bf16_f32 v53, v58, v59
	global_store_dwordx4 v[66:67], v[50:53], off offset:256
	s_nop 1
	v_add_u32_e32 v52, 0x90, v134
	v_ashrrev_i32_e32 v53, 31, v52
	v_lshlrev_b64 v[50:51], 12, v[52:53]
	v_lshlrev_b64 v[52:53], 5, v[52:53]
	v_lshl_add_u64 v[56:57], s[4:5], 0, v[52:53]
	s_nop 0
	v_lshl_add_u64 v[50:51], s[2:3], 0, v[50:51]
	v_lshl_add_u64 v[50:51], v[50:51], 0, v[136:137]
	v_mov_b32_e32 v52, v218
	v_mov_b32_e32 v53, v219
	v_mov_b32_e32 v54, v220
	v_mov_b32_e32 v55, v221
	v_mov_b32_e32 v56, v222
	v_mov_b32_e32 v57, v223
	v_mov_b32_e32 v58, v224
	v_mov_b32_e32 v59, v225
	v_mov_b32_e32 v60, v52
	v_mov_b32_e32 v61, v56
	v_mov_b32_e32 v56, v53
	v_pk_add_f32 v[52:53], v[60:61], v[56:57]
	v_mov_b32_e32 v56, v54
	v_mov_b32_e32 v57, v58
	v_mov_b32_e32 v58, v55
	v_pk_add_f32 v[54:55], v[56:57], v[58:59]
	s_nop 0
	v_pk_add_f32 v[52:53], v[52:53], v[54:55]
	s_nop 0
	v_add_f32_e32 v52, v52, v53
	v_fmamk_f32 v52, v52, 0x3a000000, v233
	v_cmp_gt_f32_e32 vcc, s11, v52
	v_mul_f32_e32 v53, 0x4f800000, v52
	s_nop 0
	v_cndmask_b32_e32 v52, v52, v53, vcc
	v_sqrt_f32_e32 v53, v52
	s_nop 0
	v_add_u32_e32 v54, -1, v53
	v_fma_f32 v55, -v54, v53, v52
	v_cmp_ge_f32_e64 s[46:47], 0, v55
	v_add_u32_e32 v55, 1, v53
	s_nop 0
	v_cndmask_b32_e64 v54, v53, v54, s[46:47]
	v_fma_f32 v53, -v55, v53, v52
	v_cmp_lt_f32_e64 s[46:47], 0, v53
	s_nop 1
	v_cndmask_b32_e64 v53, v54, v55, s[46:47]
	v_mul_f32_e32 v54, 0x37800000, v53
	v_cndmask_b32_e32 v53, v53, v54, vcc
	v_cmp_class_f32_e32 vcc, v52, v234
	s_nop 1
	v_cndmask_b32_e32 v52, v53, v52, vcc
	v_div_scale_f32 v53, s[0:1], v52, v52, 1.0
	v_rcp_f32_e32 v54, v53
	s_nop 0
	v_fma_f32 v55, -v53, v54, 1.0
	v_fmac_f32_e32 v54, v55, v54
	v_div_scale_f32 v55, vcc, 1.0, v52, 1.0
	v_mul_f32_e32 v56, v55, v54
	v_fma_f32 v57, -v53, v56, v55
	v_fmac_f32_e32 v56, v57, v54
	v_fma_f32 v53, -v53, v56, v55
	v_div_fmas_f32 v53, v53, v54, v56
	v_div_fixup_f32 v52, v53, v52, 1.0
	v_pk_mul_f32 v[48:49], v[48:49], v[52:53] op_sel_hi:[1,0]
	v_pk_mul_f32 v[46:47], v[46:47], v[52:53] op_sel_hi:[1,0]
	v_pk_mul_f32 v[54:55], v[44:45], v[52:53] op_sel_hi:[1,0]
	v_pk_mul_f32 v[44:45], v[42:43], v[52:53] op_sel_hi:[1,0]
	v_cvt_pk_bf16_f32 v42, v46, v47
	v_cvt_pk_bf16_f32 v43, v48, v49
	v_cvt_pk_bf16_f32 v44, v44, v45
	v_cvt_pk_bf16_f32 v45, v54, v55
	global_store_dwordx4 v[50:51], v[42:45], off
	v_pk_mul_f32 v[40:41], v[40:41], v[52:53] op_sel_hi:[1,0]
	v_pk_mul_f32 v[38:39], v[38:39], v[52:53] op_sel_hi:[1,0]
	v_pk_mul_f32 v[42:43], v[36:37], v[52:53] op_sel_hi:[1,0]
	v_pk_mul_f32 v[36:37], v[34:35], v[52:53] op_sel_hi:[1,0]
	v_cvt_pk_bf16_f32 v34, v38, v39
	v_cvt_pk_bf16_f32 v35, v40, v41
	v_cvt_pk_bf16_f32 v36, v36, v37
	v_cvt_pk_bf16_f32 v37, v42, v43
	global_store_dwordx4 v[50:51], v[34:37], off offset:256
	s_nop 1
	v_add_u32_e32 v36, 0xa0, v134
	v_ashrrev_i32_e32 v37, 31, v36
	v_lshlrev_b64 v[34:35], 12, v[36:37]
	v_lshlrev_b64 v[36:37], 5, v[36:37]
	v_lshl_add_u64 v[40:41], s[4:5], 0, v[36:37]
	s_nop 0
	v_lshl_add_u64 v[34:35], s[2:3], 0, v[34:35]
	v_lshl_add_u64 v[34:35], v[34:35], 0, v[136:137]
	v_mov_b32_e32 v36, v226
	v_mov_b32_e32 v37, v227
	v_mov_b32_e32 v38, v228
	v_mov_b32_e32 v39, v229
	v_mov_b32_e32 v40, v172
	v_mov_b32_e32 v41, v173
	v_mov_b32_e32 v42, v174
	v_mov_b32_e32 v43, v175
	v_mov_b32_e32 v44, v36
	v_mov_b32_e32 v45, v40
	v_mov_b32_e32 v40, v37
	v_pk_add_f32 v[36:37], v[44:45], v[40:41]
	v_mov_b32_e32 v40, v38
	v_mov_b32_e32 v41, v42
	v_mov_b32_e32 v42, v39
	v_pk_add_f32 v[38:39], v[40:41], v[42:43]
	s_nop 0
	v_pk_add_f32 v[36:37], v[36:37], v[38:39]
	s_nop 0
	v_add_f32_e32 v36, v36, v37
	v_fmamk_f32 v36, v36, 0x3a000000, v233
	v_cmp_gt_f32_e32 vcc, s11, v36
	v_mul_f32_e32 v37, 0x4f800000, v36
	s_nop 0
	v_cndmask_b32_e32 v36, v36, v37, vcc
	v_sqrt_f32_e32 v37, v36
	s_nop 0
	v_add_u32_e32 v38, -1, v37
	v_fma_f32 v39, -v38, v37, v36
	v_cmp_ge_f32_e64 s[46:47], 0, v39
	v_add_u32_e32 v39, 1, v37
	s_nop 0
	v_cndmask_b32_e64 v38, v37, v38, s[46:47]
	v_fma_f32 v37, -v39, v37, v36
	v_cmp_lt_f32_e64 s[46:47], 0, v37
	s_nop 1
	v_cndmask_b32_e64 v37, v38, v39, s[46:47]
	v_mul_f32_e32 v38, 0x37800000, v37
	v_cndmask_b32_e32 v37, v37, v38, vcc
	v_cmp_class_f32_e32 vcc, v36, v234
	s_nop 1
	v_cndmask_b32_e32 v36, v37, v36, vcc
	v_div_scale_f32 v37, s[0:1], v36, v36, 1.0
	v_rcp_f32_e32 v38, v37
	s_nop 0
	v_fma_f32 v39, -v37, v38, 1.0
	v_fmac_f32_e32 v38, v39, v38
	v_div_scale_f32 v39, vcc, 1.0, v36, 1.0
	v_mul_f32_e32 v40, v39, v38
	v_fma_f32 v41, -v37, v40, v39
	v_fmac_f32_e32 v40, v41, v38
	v_fma_f32 v37, -v37, v40, v39
	v_div_fmas_f32 v37, v37, v38, v40
	v_div_fixup_f32 v36, v37, v36, 1.0
	v_pk_mul_f32 v[32:33], v[32:33], v[36:37] op_sel_hi:[1,0]
	v_pk_mul_f32 v[30:31], v[30:31], v[36:37] op_sel_hi:[1,0]
	v_pk_mul_f32 v[38:39], v[28:29], v[36:37] op_sel_hi:[1,0]
	v_pk_mul_f32 v[28:29], v[26:27], v[36:37] op_sel_hi:[1,0]
	v_cvt_pk_bf16_f32 v26, v30, v31
	v_cvt_pk_bf16_f32 v27, v32, v33
	v_cvt_pk_bf16_f32 v28, v28, v29
	v_cvt_pk_bf16_f32 v29, v38, v39
	global_store_dwordx4 v[34:35], v[26:29], off
	v_pk_mul_f32 v[24:25], v[24:25], v[36:37] op_sel_hi:[1,0]
	v_pk_mul_f32 v[22:23], v[22:23], v[36:37] op_sel_hi:[1,0]
	v_pk_mul_f32 v[26:27], v[20:21], v[36:37] op_sel_hi:[1,0]
	v_pk_mul_f32 v[20:21], v[18:19], v[36:37] op_sel_hi:[1,0]
	v_cvt_pk_bf16_f32 v18, v22, v23
	v_cvt_pk_bf16_f32 v19, v24, v25
	v_cvt_pk_bf16_f32 v20, v20, v21
	v_cvt_pk_bf16_f32 v21, v26, v27
	global_store_dwordx4 v[34:35], v[18:21], off offset:256
	s_nop 1
	v_add_u32_e32 v20, 0xb0, v134
	v_ashrrev_i32_e32 v21, 31, v20
	v_lshlrev_b64 v[18:19], 12, v[20:21]
	v_lshlrev_b64 v[20:21], 5, v[20:21]
	v_lshl_add_u64 v[24:25], s[4:5], 0, v[20:21]
	s_nop 0
	v_lshl_add_u64 v[18:19], s[2:3], 0, v[18:19]
	v_lshl_add_u64 v[18:19], v[18:19], 0, v[136:137]
	s_mov_b32 s2, s10
	s_waitcnt vmcnt(8)
	v_mov_b32_e32 v20, v186
	v_mov_b32_e32 v21, v187
	v_mov_b32_e32 v22, v188
	v_mov_b32_e32 v23, v189
	v_mov_b32_e32 v24, v190
	v_mov_b32_e32 v25, v191
	v_mov_b32_e32 v26, v192
	v_mov_b32_e32 v27, v193
	v_mov_b32_e32 v28, v20
	v_mov_b32_e32 v29, v24
	v_mov_b32_e32 v24, v21
	v_pk_add_f32 v[20:21], v[28:29], v[24:25]
	v_mov_b32_e32 v24, v22
	v_mov_b32_e32 v25, v26
	v_mov_b32_e32 v26, v23
	v_pk_add_f32 v[22:23], v[24:25], v[26:27]
	s_nop 0
	v_pk_add_f32 v[20:21], v[20:21], v[22:23]
	s_nop 0
	v_add_f32_e32 v20, v20, v21
	v_fmamk_f32 v20, v20, 0x3a000000, v233
	v_cmp_gt_f32_e32 vcc, s11, v20
	v_mul_f32_e32 v21, 0x4f800000, v20
	s_nop 0
	v_cndmask_b32_e32 v20, v20, v21, vcc
	v_sqrt_f32_e32 v21, v20
	s_nop 0
	v_add_u32_e32 v22, -1, v21
	v_fma_f32 v23, -v22, v21, v20
	v_cmp_ge_f32_e64 s[46:47], 0, v23
	v_add_u32_e32 v23, 1, v21
	s_nop 0
	v_cndmask_b32_e64 v22, v21, v22, s[46:47]
	v_fma_f32 v21, -v23, v21, v20
	v_cmp_lt_f32_e64 s[46:47], 0, v21
	s_nop 1
	v_cndmask_b32_e64 v21, v22, v23, s[46:47]
	v_mul_f32_e32 v22, 0x37800000, v21
	v_cndmask_b32_e32 v21, v21, v22, vcc
	v_cmp_class_f32_e32 vcc, v20, v234
	s_mov_b32 s46, s14
	s_nop 0
	v_cndmask_b32_e32 v20, v21, v20, vcc
	v_div_scale_f32 v21, s[0:1], v20, v20, 1.0
	v_rcp_f32_e32 v22, v21
	s_mov_b64 s[0:1], s[24:25]
	v_fma_f32 v23, -v21, v22, 1.0
	v_fmac_f32_e32 v22, v23, v22
	v_div_scale_f32 v23, vcc, 1.0, v20, 1.0
	v_mul_f32_e32 v24, v23, v22
	v_fma_f32 v25, -v21, v24, v23
	v_fmac_f32_e32 v24, v25, v22
	v_fma_f32 v21, -v21, v24, v23
	v_div_fmas_f32 v21, v21, v22, v24
	v_div_fixup_f32 v20, v21, v20, 1.0
	v_pk_mul_f32 v[16:17], v[16:17], v[20:21] op_sel_hi:[1,0]
	v_pk_mul_f32 v[14:15], v[14:15], v[20:21] op_sel_hi:[1,0]
	v_pk_mul_f32 v[22:23], v[12:13], v[20:21] op_sel_hi:[1,0]
	v_pk_mul_f32 v[12:13], v[10:11], v[20:21] op_sel_hi:[1,0]
	v_cvt_pk_bf16_f32 v10, v14, v15
	v_cvt_pk_bf16_f32 v11, v16, v17
	v_cvt_pk_bf16_f32 v12, v12, v13
	v_cvt_pk_bf16_f32 v13, v22, v23
	global_store_dwordx4 v[18:19], v[10:13], off
	v_pk_mul_f32 v[8:9], v[8:9], v[20:21] op_sel_hi:[1,0]
	v_pk_mul_f32 v[6:7], v[6:7], v[20:21] op_sel_hi:[1,0]
	v_pk_mul_f32 v[10:11], v[4:5], v[20:21] op_sel_hi:[1,0]
	v_pk_mul_f32 v[4:5], v[2:3], v[20:21] op_sel_hi:[1,0]
	v_cvt_pk_bf16_f32 v2, v6, v7
	v_cvt_pk_bf16_f32 v3, v8, v9
	v_cvt_pk_bf16_f32 v4, v4, v5
	v_cvt_pk_bf16_f32 v5, v10, v11
	s_and_b64 vcc, exec, s[42:43]
	global_store_dwordx4 v[18:19], v[2:5], off offset:256
	s_cbranch_vccz .LBB0_97
	s_waitcnt vmcnt(0)
	s_cmpk_gt_u32 s55, 0xff
	s_cbranch_scc1 .LBB0_108
	s_barrier
